# adds: merge GEMM K-loop rewritten with the interleaved schedule (single register stage, accumulator restart per branch, hipcc gating blocks kept between branches)
# baseline (speedup 1.0000x reference)
.LBB0_7:
	v_writelane_b32 v251, s0, 5
	s_nop 1
	v_writelane_b32 v251, s1, 6
	s_nop 0
	v_readlane_b32 s0, v251, 3
	v_readlane_b32 s1, v251, 4
	s_cmp_le_i32 s1, s0
	s_cbranch_scc1 .Lexit_near
	v_readlane_b32 s16, v251, 5
	v_readlane_b32 s17, v251, 6
	s_load_dwordx2 s[18:19], s[16:17], 0x130
	s_load_dwordx4 s[0:3], s[16:17], 0x120
	s_load_dwordx8 s[64:71], s[16:17], 0x100
	s_load_dwordx8 s[8:15], s[16:17], 0x240
	v_mov_b32_e32 v3, 0
	v_mbcnt_lo_u32_b32 v2, -1, 0
	v_mov_b32_e32 v1, 0x358637bd
	s_waitcnt lgkmcnt(0)
	v_writelane_b32 v251, s0, 7
	v_mov_b32_e32 v197, 0x12010
	v_mov_b32_e32 v191, 0x3c0881c4
	v_writelane_b32 v251, s1, 8
	v_writelane_b32 v251, s2, 9
	v_writelane_b32 v251, s3, 10
	v_mov_b32_e32 v192, 0xbab64f3b
	v_readlane_b32 s2, v251, 0
	s_cmpk_lt_i32 s2, 0xb00
	s_cselect_b64 s[0:1], -1, 0
	v_writelane_b32 v251, s0, 11
	v_mbcnt_hi_u32_b32 v190, -1, v2
	v_mov_b32_e32 v201, 0xf149f2ca
	v_writelane_b32 v251, s1, 12
	s_lshl_b32 s0, s2, 18
	s_and_b32 s0, s0, 0xfc0000
	s_add_u32 s0, s14, s0
	s_addc_u32 s1, s15, 0
	v_writelane_b32 v251, s0, 13
	v_mov_b32_e32 v202, 0xb000
	v_mov_b32_e32 v204, 0xffffa800
	v_writelane_b32 v251, s1, 14
	s_ashr_i32 s0, s2, 6
	s_ashr_i32 s1, s0, 31
	s_lshl_b64 s[6:7], s[0:1], 17
	s_add_u32 s62, s16, 0x268
	v_writelane_b32 v251, s6, 15
	s_addc_u32 s63, s17, 0
	s_lshl_b32 s3, s2, 2
	v_writelane_b32 v251, s7, 16
	s_cmpk_lt_i32 s2, 0x200
	v_writelane_b32 v251, s3, 17
	s_cselect_b64 s[6:7], -1, 0
	v_writelane_b32 v251, s6, 18
	s_cmpk_lt_i32 s2, 0xd00
	v_mov_b32_e32 v205, 0x10800
	v_writelane_b32 v251, s7, 19
	s_cselect_b64 s[6:7], -1, 0
	v_writelane_b32 v251, s6, 20
	s_lshl_b64 s[0:1], s[0:1], 18
	s_cmpk_lt_i32 s2, 0xe10
	v_writelane_b32 v251, s7, 21
	v_writelane_b32 v251, s0, 22
	v_mov_b32_e32 v206, 0x16000
	v_mov_b32_e32 v207, 0x5800
	v_writelane_b32 v251, s1, 23
	s_cselect_b64 s[0:1], -1, 0
	v_writelane_b32 v251, s0, 24
	v_mov_b32_e32 v208, 0x7f
	v_mov_b32_e32 v209, 0x42800000
	v_writelane_b32 v251, s1, 25
	s_add_u32 s0, s70, 0x6800000
	v_writelane_b32 v251, s0, 26
	s_addc_u32 s0, s71, 0
	v_writelane_b32 v251, s0, 27
	s_add_u32 s0, s70, 0x6000000
	v_writelane_b32 v251, s0, 28
	s_addc_u32 s0, s71, 0
	v_writelane_b32 v251, s0, 29
	s_add_u32 s0, s18, 0x2000
	s_addc_u32 s1, s19, 0
	v_writelane_b32 v251, s0, 30
	v_not_b32_e32 v210, 63
	v_not_b32_e32 v211, 31
	v_writelane_b32 v251, s1, 31
	s_add_u32 s0, s18, 0x2800
	s_addc_u32 s1, s19, 0
	v_writelane_b32 v251, s0, 32
	v_mov_b32_e32 v212, 0x7fc00000
	s_mov_b32 s33, 0x10000
	v_writelane_b32 v251, s1, 33
	s_add_u32 s0, s18, 0x1000
	s_addc_u32 s1, s19, 0
	v_writelane_b32 v251, s0, 34
	s_cmpk_lt_i32 s2, 0x180
	s_mov_b32 s78, 0x20000
	v_writelane_b32 v251, s1, 35
	s_cselect_b64 s[0:1], -1, 0
	v_writelane_b32 v251, s0, 36
	s_mov_b32 s79, 0x30000
	s_mov_b32 s83, 0xfffffc0
	v_writelane_b32 v251, s1, 37
	s_lshl_b32 s0, s2, 8
	s_cmpk_lt_i32 s2, 0x4280
	v_writelane_b32 v251, s0, 38
	s_cselect_b64 s[0:1], -1, 0
	v_writelane_b32 v251, s0, 39
	s_movk_i32 s41, 0x90
	s_movk_i32 s92, 0x80
	v_writelane_b32 v251, s1, 40
	s_add_u32 s0, s16, 48
	s_addc_u32 s1, s17, 0
	v_writelane_b32 v251, s0, 41
	s_movk_i32 s73, 0x1600
	s_movk_i32 s74, 0x7f
	v_writelane_b32 v251, s1, 42
	s_add_u32 s0, s16, 40
	s_addc_u32 s1, s17, 0
	v_writelane_b32 v251, s0, 43
	s_movk_i32 s75, 0x2000
	s_movk_i32 s76, 0xfff
	v_writelane_b32 v251, s1, 44
	s_add_u32 s0, s16, 56
	s_addc_u32 s1, s17, 0
	v_writelane_b32 v251, s0, 45
	s_movk_i32 s80, 0x6000
	s_movk_i32 s77, 0x4000
	v_writelane_b32 v251, s1, 46
	s_add_u32 s0, s16, 32
	s_addc_u32 s1, s17, 0
	v_writelane_b32 v251, s0, 47
	s_mov_b32 s86, 0x800000
	s_movk_i32 s36, 0x1fff
	v_writelane_b32 v251, s1, 48
	s_add_u32 s0, s16, 0x1f0
	s_addc_u32 s1, s17, 0
	v_writelane_b32 v251, s0, 49
	s_mov_b32 s72, 0x40000
	s_movk_i32 s81, 0x3ff
	v_writelane_b32 v251, s1, 50
	s_add_u32 s0, s16, 0x1e8
	s_addc_u32 s1, s17, 0
	v_writelane_b32 v251, s0, 51
	s_movk_i32 s82, 0x81
	s_mov_b32 s43, 0
	v_writelane_b32 v251, s1, 52
	s_add_u32 s0, s16, 0x1f8
	s_addc_u32 s1, s17, 0
	v_writelane_b32 v251, s0, 53
	s_mov_b64 s[60:61], 0x100
	s_nop 0
	v_writelane_b32 v251, s1, 54
	s_add_u32 s0, s16, 0x1e0
	s_addc_u32 s1, s17, 0
	v_writelane_b32 v251, s0, 55
	s_nop 1
	v_writelane_b32 v251, s1, 56
	s_add_u32 s0, s16, 0x1d8
	s_addc_u32 s1, s17, 0
	v_writelane_b32 v251, s0, 57
	s_add_u32 s20, s16, 0x1d0
	s_addc_u32 s21, s17, 0
	v_writelane_b32 v251, s1, 58
	s_nop 0
	v_readlane_b32 s6, v251, 1
	v_readlane_b32 s7, v251, 2
	s_add_u32 s0, s6, 0x200
	s_addc_u32 s1, s7, 0
	v_writelane_b32 v251, s0, 59
	s_nop 1
	v_writelane_b32 v251, s1, 60
	s_add_u32 s0, s6, 0x1000
	s_addc_u32 s1, s7, 0
	v_writelane_b32 v251, s0, 61
	s_nop 1
	v_writelane_b32 v251, s1, 62
	s_add_u32 s0, s6, 0x1100
	s_addc_u32 s1, s7, 0
	v_writelane_b32 v251, s0, 63
	s_nop 1
	v_writelane_b32 v252, s1, 0
	s_add_u32 s0, s6, 0x1200
	s_addc_u32 s1, s7, 0
	v_writelane_b32 v252, s0, 1
	s_nop 1
	v_writelane_b32 v252, s1, 2
	s_add_u32 s0, s6, 0x1300
	s_addc_u32 s1, s7, 0
	v_writelane_b32 v252, s0, 3
	s_cmp_eq_u32 s4, 15
	s_nop 0
	v_writelane_b32 v252, s1, 4
	s_cselect_b64 s[0:1], -1, 0
	v_writelane_b32 v252, s0, 5
	s_cmp_eq_u32 s4, 14
	s_nop 0
	v_writelane_b32 v252, s1, 6
	s_cselect_b64 s[0:1], -1, 0
	v_writelane_b32 v252, s0, 7
	s_cmp_eq_u32 s4, 13
	s_nop 0
	v_writelane_b32 v252, s1, 8
	s_cselect_b64 s[0:1], -1, 0
	v_writelane_b32 v252, s0, 9
	s_cmp_eq_u32 s4, 12
	s_nop 0
	v_writelane_b32 v252, s1, 10
	s_cselect_b64 s[0:1], -1, 0
	v_writelane_b32 v252, s0, 11
	s_cmp_eq_u32 s4, 11
	s_nop 0
	v_writelane_b32 v252, s1, 12
	s_cselect_b64 s[0:1], -1, 0
	v_writelane_b32 v252, s0, 13
	s_cmp_eq_u32 s4, 10
	s_nop 0
	v_writelane_b32 v252, s1, 14
	s_cselect_b64 s[0:1], -1, 0
	v_writelane_b32 v252, s0, 15
	s_cmp_eq_u32 s4, 9
	s_nop 0
	v_writelane_b32 v252, s1, 16
	s_cselect_b64 s[0:1], -1, 0
	v_writelane_b32 v252, s0, 17
	s_cmp_eq_u32 s4, 8
	s_nop 0
	v_writelane_b32 v252, s1, 18
	s_cselect_b64 s[0:1], -1, 0
	v_writelane_b32 v252, s0, 19
	s_cmp_eq_u32 s4, 7
	s_nop 0
	v_writelane_b32 v252, s1, 20
	s_cselect_b64 s[0:1], -1, 0
	v_writelane_b32 v252, s0, 21
	s_cmp_eq_u32 s4, 6
	s_nop 0
	v_writelane_b32 v252, s1, 22
	s_cselect_b64 s[0:1], -1, 0
	v_writelane_b32 v252, s0, 23
	s_cmp_eq_u32 s4, 5
	s_nop 0
	v_writelane_b32 v252, s1, 24
	s_cselect_b64 s[0:1], -1, 0
	v_writelane_b32 v252, s0, 25
	s_cmp_eq_u32 s4, 4
	s_nop 0
	v_writelane_b32 v252, s1, 26
	s_cselect_b64 s[0:1], -1, 0
	v_writelane_b32 v252, s0, 27
	s_cmp_eq_u32 s4, 3
	s_nop 0
	v_writelane_b32 v252, s1, 28
	s_cselect_b64 s[0:1], -1, 0
	v_writelane_b32 v252, s0, 29
	s_cmp_eq_u32 s4, 2
	s_nop 0
	v_writelane_b32 v252, s1, 30
	s_cselect_b64 s[0:1], -1, 0
	v_writelane_b32 v252, s0, 31
	s_cmp_eq_u32 s4, 1
	s_nop 0
	v_writelane_b32 v252, s1, 32
	s_cselect_b64 s[0:1], -1, 0
	v_writelane_b32 v252, s0, 33
	s_cmp_eq_u32 s4, 0
	s_nop 0
	v_writelane_b32 v252, s1, 34
	s_cselect_b64 s[0:1], -1, 0
	v_writelane_b32 v252, s0, 35
	s_nop 1
	v_writelane_b32 v252, s1, 36
	s_lshl_b32 s0, s4, 8
	s_add_u32 s0, s6, s0
	s_addc_u32 s1, s7, 0
	s_add_u32 s4, s0, 0x1400
	s_addc_u32 s5, s1, 0
	v_writelane_b32 v252, s4, 37
	s_add_u32 s0, s0, 0x2400
	s_addc_u32 s1, s1, 0
	v_writelane_b32 v252, s5, 38
	v_writelane_b32 v252, s0, 39
	s_nop 1
	v_writelane_b32 v252, s1, 40
	s_add_u32 s0, s6, 0x3400
	s_addc_u32 s1, s7, 0
	v_writelane_b32 v252, s0, 41
	s_nop 1
	v_writelane_b32 v252, s1, 42
	s_add_u32 s0, s6, 0x3500
	s_addc_u32 s1, s7, 0
	v_writelane_b32 v252, s0, 43
	s_nop 1
	v_writelane_b32 v252, s1, 44
	s_add_u32 s0, s70, 0x800
	s_addc_u32 s1, s71, 0
	v_writelane_b32 v252, s0, 45
	s_nop 1
	v_writelane_b32 v252, s1, 46
	s_add_u32 s0, s14, 0x400
	v_writelane_b32 v252, s8, 47
	s_addc_u32 s1, s15, 0
	s_nop 0
	v_writelane_b32 v252, s9, 48
	v_writelane_b32 v252, s10, 49
	v_writelane_b32 v252, s11, 50
	v_writelane_b32 v252, s12, 51
	v_writelane_b32 v252, s13, 52
	v_writelane_b32 v252, s14, 53
	v_writelane_b32 v252, s15, 54
	v_writelane_b32 v252, s0, 55
	s_nop 1
	v_writelane_b32 v252, s1, 56
	s_lshl_b32 s0, s2, 9
	v_writelane_b32 v252, s0, 57
	v_cmp_eq_u32_e64 s[0:1], 0, v0
	s_nop 1
	v_writelane_b32 v252, s0, 58
	s_nop 1
	v_writelane_b32 v252, s1, 59
	s_load_dwordx2 s[0:1], s[16:17], 0x1c8
	s_waitcnt lgkmcnt(0)
	v_writelane_b32 v252, s0, 60
	s_nop 1
	v_writelane_b32 v252, s1, 61
	s_load_dwordx4 s[0:3], s[16:17], 0x1b0
	s_waitcnt lgkmcnt(0)
	v_writelane_b32 v252, s0, 62
	s_nop 1
	v_writelane_b32 v253, s2, 0
	v_writelane_b32 v252, s1, 63
	v_writelane_b32 v253, s3, 1
	s_load_dwordx8 s[0:7], s[16:17], 0x190
	s_waitcnt lgkmcnt(0)
	v_writelane_b32 v253, s0, 2
	s_nop 1
	v_writelane_b32 v253, s1, 3
	v_writelane_b32 v253, s2, 4
	v_writelane_b32 v253, s3, 5
	v_writelane_b32 v253, s4, 6
	v_writelane_b32 v253, s5, 7
	v_writelane_b32 v253, s6, 8
	v_writelane_b32 v253, s7, 9
	s_load_dwordx8 s[0:7], s[16:17], 0x0
	s_waitcnt lgkmcnt(0)
	v_writelane_b32 v253, s0, 10
	s_nop 1
	v_writelane_b32 v253, s1, 11
	v_writelane_b32 v253, s2, 12
	v_writelane_b32 v253, s3, 13
	v_writelane_b32 v253, s4, 14
	v_writelane_b32 v253, s5, 15
	v_writelane_b32 v253, s6, 16
	v_writelane_b32 v253, s7, 17
	s_load_dwordx8 s[0:7], s[16:17], 0x140
	s_waitcnt lgkmcnt(0)
	v_writelane_b32 v253, s0, 18
	s_nop 1
	v_writelane_b32 v253, s1, 19
	v_writelane_b32 v253, s2, 20
	v_writelane_b32 v253, s3, 21
	v_writelane_b32 v253, s4, 22
	v_writelane_b32 v253, s5, 23
	v_writelane_b32 v253, s6, 24
	v_writelane_b32 v253, s7, 25
	s_load_dwordx16 s[0:15], s[16:17], 0x200
	s_waitcnt lgkmcnt(0)
	v_writelane_b32 v253, s0, 26
	s_nop 1
	v_writelane_b32 v253, s1, 27
	v_writelane_b32 v253, s2, 28
	v_writelane_b32 v253, s3, 29
	v_writelane_b32 v253, s4, 30
	v_writelane_b32 v253, s5, 31
	v_writelane_b32 v253, s6, 32
	v_writelane_b32 v253, s7, 33
	v_writelane_b32 v253, s8, 34
	v_writelane_b32 v253, s9, 35
	v_writelane_b32 v253, s10, 36
	v_writelane_b32 v253, s11, 37
	v_writelane_b32 v253, s12, 38
	v_writelane_b32 v253, s13, 39
	v_writelane_b32 v253, s14, 40
	v_writelane_b32 v253, s15, 41
	s_load_dwordx16 s[44:59], s[16:17], 0x40
	s_load_dwordx16 s[0:15], s[16:17], 0xc0
	s_waitcnt lgkmcnt(0)
	v_writelane_b32 v253, s0, 42
	s_nop 1
	v_writelane_b32 v253, s1, 43
	v_writelane_b32 v253, s2, 44
	v_writelane_b32 v253, s3, 45
	v_writelane_b32 v253, s4, 46
	v_writelane_b32 v253, s5, 47
	v_writelane_b32 v253, s6, 48
	v_writelane_b32 v253, s7, 49
	v_writelane_b32 v253, s8, 50
	v_writelane_b32 v253, s9, 51
	v_writelane_b32 v253, s10, 52
	v_writelane_b32 v253, s11, 53
	v_writelane_b32 v253, s12, 54
	v_writelane_b32 v253, s13, 55
	v_writelane_b32 v253, s14, 56
	v_writelane_b32 v253, s15, 57
	s_load_dwordx16 s[0:15], s[16:17], 0x80
	s_waitcnt lgkmcnt(0)
	v_writelane_b32 v253, s0, 58
	s_nop 1
	v_writelane_b32 v254, s6, 0
	v_writelane_b32 v254, s7, 1
	v_writelane_b32 v254, s8, 2
	v_writelane_b32 v254, s9, 3
	v_writelane_b32 v254, s10, 4
	v_writelane_b32 v254, s11, 5
	v_writelane_b32 v254, s12, 6
	v_writelane_b32 v254, s13, 7
	v_writelane_b32 v254, s14, 8
	v_writelane_b32 v254, s15, 9
	v_writelane_b32 v254, s18, 10
	v_writelane_b32 v253, s1, 59
	v_writelane_b32 v253, s2, 60
	v_writelane_b32 v254, s19, 11
	v_writelane_b32 v254, s64, 12
	v_writelane_b32 v253, s3, 61
	v_writelane_b32 v253, s4, 62
	v_writelane_b32 v254, s65, 13
	v_writelane_b32 v254, s66, 14
	v_writelane_b32 v254, s67, 15
	v_writelane_b32 v254, s68, 16
	v_writelane_b32 v254, s69, 17
	v_writelane_b32 v254, s70, 18
	v_writelane_b32 v254, s71, 19
	v_writelane_b32 v254, s62, 20
	v_writelane_b32 v253, s5, 63
	s_nop 0
	v_writelane_b32 v254, s63, 21
	v_writelane_b32 v254, s20, 22
	s_nop 1
	v_writelane_b32 v254, s21, 23
	s_branch .LBB0_12
.Lexit_near:
	s_endpgm
.LBB0_9:
	s_or_b64 exec, exec, s[2:3]
	v_readlane_b32 s2, v252, 39
	v_readlane_b32 s3, v252, 40
	v_mov_b32_e32 v2, 1
	s_waitcnt vmcnt(0)
	buffer_inv sc1
	s_nop 1
	global_atomic_add v3, v2, s[2:3]
	s_waitcnt vmcnt(0)

.LBB0_63:
	s_mov_b32 s6, 0x10000
	s_mov_b32 s7, 0
	v_lshl_add_u64 v[240:241], s[6:7], 0, v[118:119]
	s_mov_b32 s6, 0x20000
	s_mov_b32 s7, 0
	v_lshl_add_u64 v[242:243], s[6:7], 0, v[118:119]
	s_mov_b32 s6, 0x30000
	s_mov_b32 s7, 0
	v_lshl_add_u64 v[244:245], s[6:7], 0, v[118:119]
	s_mov_b32 s6, 0x10000
	s_mov_b32 s7, 0
	v_lshl_add_u64 v[246:247], s[6:7], 0, v[122:123]
	s_mov_b32 s6, 0x20000
	s_mov_b32 s7, 0
	v_lshl_add_u64 v[248:249], s[6:7], 0, v[122:123]
	s_mov_b32 s6, 0x30000
	s_mov_b32 s7, 0
	v_lshl_add_u64 v[188:189], s[6:7], 0, v[122:123]
	v_lshrrev_b32_e32 v236, 3, v0
	v_lshlrev_b32_e32 v237, 4, v0
	v_mul_u32_u24_e32 v236, 0x90, v236
	v_and_b32_e32 v237, 0x70, v237
	v_add_u32_e32 v194, v236, v237
	v_add_u32_e32 v195, 0x9000, v194
	v_lshrrev_b32_e32 v236, 1, v0
	v_and_b32_e32 v237, 31, v0
	v_and_b32_e32 v238, 16, v236
	v_and_b32_e32 v236, 64, v236
	v_add_u32_e32 v236, v236, v237
	v_mul_u32_u24_e32 v236, 0x90, v236
	v_add_u32_e32 v196, v236, v238
	v_and_b32_e32 v236, 64, v0
	v_add_u32_e32 v236, v236, v237
	v_mul_u32_u24_e32 v236, 0x90, v236
	v_add_u32_e32 v197, v236, v238
	s_barrier
	s_waitcnt vmcnt(7)
	ds_write_b128 v194, v[68:71]
	s_waitcnt vmcnt(5)
	ds_write_b128 v194, v[76:79] offset:4608
	s_waitcnt vmcnt(3)
	ds_write_b128 v194, v[84:87] offset:9216
	s_waitcnt vmcnt(1)
	ds_write_b128 v194, v[92:95] offset:13824
	ds_write_b128 v194, v[72:75] offset:18432
	ds_write_b128 v194, v[80:83] offset:23040
	ds_write_b128 v194, v[88:91] offset:27648
	s_waitcnt vmcnt(0)
	ds_write_b128 v194, v[96:99] offset:32256
	global_load_dwordx4 v[68:71], v[118:119], off offset:128
	global_load_dwordx4 v[76:79], v[240:241], off offset:128
	global_load_dwordx4 v[84:87], v[242:243], off offset:128
	global_load_dwordx4 v[92:95], v[244:245], off offset:128
	global_load_dwordx4 v[72:75], v[122:123], off offset:128
	global_load_dwordx4 v[80:83], v[246:247], off offset:128
	global_load_dwordx4 v[88:91], v[248:249], off offset:128
	global_load_dwordx4 v[96:99], v[188:189], off offset:128
	s_waitcnt lgkmcnt(0)
	s_barrier
	ds_read_b128 v[180:183], v196
	ds_read_b128 v[184:187], v197 offset:18432
	ds_read_b128 v[216:219], v197 offset:23040
	ds_read_b128 v[220:223], v196 offset:4608
	ds_read_b128 v[224:227], v196 offset:32
	ds_read_b128 v[228:231], v197 offset:18464
	ds_read_b128 v[232:235], v197 offset:23072
	ds_read_b128 v[236:239], v196 offset:4640
	s_setprio 1
	s_waitcnt lgkmcnt(6)
	v_mfma_f32_32x32x16_bf16 v[52:67], v[184:187], v[180:183], 0
	s_waitcnt vmcnt(7)
	ds_write_b128 v195, v[68:71]
	s_waitcnt lgkmcnt(6)
	v_mfma_f32_32x32x16_bf16 v[36:51], v[216:219], v[180:183], 0
	s_waitcnt vmcnt(6)
	ds_write_b128 v195, v[76:79] offset:4608
	s_waitcnt lgkmcnt(6)
	v_mfma_f32_32x32x16_bf16 v[20:35], v[184:187], v[220:223], 0
	s_waitcnt vmcnt(5)
	ds_write_b128 v195, v[84:87] offset:9216
	global_load_dwordx4 v[68:71], v[118:119], off offset:256
	v_mfma_f32_32x32x16_bf16 v[4:19], v[216:219], v[220:223], 0
	ds_read_b128 v[180:183], v196 offset:64
	ds_read_b128 v[184:187], v197 offset:18496
	s_waitcnt lgkmcnt(7)
	v_mfma_f32_32x32x16_bf16 v[52:67], v[228:231], v[224:227], v[52:67]
	ds_read_b128 v[216:219], v197 offset:23104
	ds_read_b128 v[220:223], v196 offset:4672
	s_waitcnt lgkmcnt(8)
	v_mfma_f32_32x32x16_bf16 v[36:51], v[232:235], v[224:227], v[36:51]
	s_waitcnt vmcnt(5)
	ds_write_b128 v195, v[92:95] offset:13824
	global_load_dwordx4 v[76:79], v[240:241], off offset:256
	s_waitcnt lgkmcnt(8)
	v_mfma_f32_32x32x16_bf16 v[20:35], v[228:231], v[236:239], v[20:35]
	s_waitcnt vmcnt(5)
	ds_write_b128 v195, v[72:75] offset:18432
	global_load_dwordx4 v[84:87], v[242:243], off offset:256
	v_mfma_f32_32x32x16_bf16 v[4:19], v[232:235], v[236:239], v[4:19]
	ds_read_b128 v[224:227], v196 offset:96
	ds_read_b128 v[228:231], v197 offset:18528
	s_waitcnt lgkmcnt(6)
	v_mfma_f32_32x32x16_bf16 v[52:67], v[184:187], v[180:183], v[52:67]
	ds_read_b128 v[232:235], v197 offset:23136
	ds_read_b128 v[236:239], v196 offset:4704
	s_waitcnt lgkmcnt(7)
	v_mfma_f32_32x32x16_bf16 v[36:51], v[216:219], v[180:183], v[36:51]
	s_waitcnt vmcnt(5)
	ds_write_b128 v195, v[80:83] offset:23040
	global_load_dwordx4 v[92:95], v[244:245], off offset:256
	s_waitcnt lgkmcnt(7)
	v_mfma_f32_32x32x16_bf16 v[20:35], v[184:187], v[220:223], v[20:35]
	s_waitcnt vmcnt(5)
	ds_write_b128 v195, v[88:91] offset:27648
	global_load_dwordx4 v[72:75], v[122:123], off offset:256
	v_mfma_f32_32x32x16_bf16 v[4:19], v[216:219], v[220:223], v[4:19]
	s_waitcnt vmcnt(5)
	ds_write_b128 v195, v[96:99] offset:32256
	global_load_dwordx4 v[80:83], v[246:247], off offset:256
	s_waitcnt lgkmcnt(5)
	v_mfma_f32_32x32x16_bf16 v[52:67], v[228:231], v[224:227], v[52:67]
	global_load_dwordx4 v[88:91], v[248:249], off offset:256
	s_waitcnt lgkmcnt(4)
	v_mfma_f32_32x32x16_bf16 v[36:51], v[232:235], v[224:227], v[36:51]
	global_load_dwordx4 v[96:99], v[188:189], off offset:256
	s_waitcnt lgkmcnt(3)
	v_mfma_f32_32x32x16_bf16 v[20:35], v[228:231], v[236:239], v[20:35]
	v_mfma_f32_32x32x16_bf16 v[4:19], v[232:235], v[236:239], v[4:19]
	s_setprio 0
	s_waitcnt lgkmcnt(0)
	s_barrier
	ds_read_b128 v[180:183], v196 offset:36864
	ds_read_b128 v[184:187], v197 offset:55296
	ds_read_b128 v[216:219], v197 offset:59904
	ds_read_b128 v[220:223], v196 offset:41472
	ds_read_b128 v[224:227], v196 offset:36896
	ds_read_b128 v[228:231], v197 offset:55328
	ds_read_b128 v[232:235], v197 offset:59936
	ds_read_b128 v[236:239], v196 offset:41504
	s_setprio 1
	s_waitcnt lgkmcnt(6)
	v_mfma_f32_32x32x16_bf16 v[52:67], v[184:187], v[180:183], v[52:67]
	s_waitcnt vmcnt(7)
	ds_write_b128 v194, v[68:71]
	s_waitcnt lgkmcnt(6)
	v_mfma_f32_32x32x16_bf16 v[36:51], v[216:219], v[180:183], v[36:51]
	s_waitcnt vmcnt(6)
	ds_write_b128 v194, v[76:79] offset:4608
	s_waitcnt lgkmcnt(6)
	v_mfma_f32_32x32x16_bf16 v[20:35], v[184:187], v[220:223], v[20:35]
	s_waitcnt vmcnt(5)
	ds_write_b128 v194, v[84:87] offset:9216
	global_load_dwordx4 v[68:71], v[118:119], off offset:384
	v_mfma_f32_32x32x16_bf16 v[4:19], v[216:219], v[220:223], v[4:19]
	ds_read_b128 v[180:183], v196 offset:36928
	ds_read_b128 v[184:187], v197 offset:55360
	s_waitcnt lgkmcnt(7)
	v_mfma_f32_32x32x16_bf16 v[52:67], v[228:231], v[224:227], v[52:67]
	ds_read_b128 v[216:219], v197 offset:59968
	ds_read_b128 v[220:223], v196 offset:41536
	s_waitcnt lgkmcnt(8)
	v_mfma_f32_32x32x16_bf16 v[36:51], v[232:235], v[224:227], v[36:51]
	s_waitcnt vmcnt(5)
	ds_write_b128 v194, v[92:95] offset:13824
	global_load_dwordx4 v[76:79], v[240:241], off offset:384
	s_waitcnt lgkmcnt(8)
	v_mfma_f32_32x32x16_bf16 v[20:35], v[228:231], v[236:239], v[20:35]
	s_waitcnt vmcnt(5)
	ds_write_b128 v194, v[72:75] offset:18432
	global_load_dwordx4 v[84:87], v[242:243], off offset:384
	v_mfma_f32_32x32x16_bf16 v[4:19], v[232:235], v[236:239], v[4:19]
	ds_read_b128 v[224:227], v196 offset:36960
	ds_read_b128 v[228:231], v197 offset:55392
	s_waitcnt lgkmcnt(6)
	v_mfma_f32_32x32x16_bf16 v[52:67], v[184:187], v[180:183], v[52:67]
	ds_read_b128 v[232:235], v197 offset:60000
	ds_read_b128 v[236:239], v196 offset:41568
	s_waitcnt lgkmcnt(7)
	v_mfma_f32_32x32x16_bf16 v[36:51], v[216:219], v[180:183], v[36:51]
	s_waitcnt vmcnt(5)
	ds_write_b128 v194, v[80:83] offset:23040
	global_load_dwordx4 v[92:95], v[244:245], off offset:384
	s_waitcnt lgkmcnt(7)
	v_mfma_f32_32x32x16_bf16 v[20:35], v[184:187], v[220:223], v[20:35]
	s_waitcnt vmcnt(5)
	ds_write_b128 v194, v[88:91] offset:27648
	global_load_dwordx4 v[72:75], v[122:123], off offset:384
	v_mfma_f32_32x32x16_bf16 v[4:19], v[216:219], v[220:223], v[4:19]
	s_waitcnt vmcnt(5)
	ds_write_b128 v194, v[96:99] offset:32256
	global_load_dwordx4 v[80:83], v[246:247], off offset:384
	s_waitcnt lgkmcnt(5)
	v_mfma_f32_32x32x16_bf16 v[52:67], v[228:231], v[224:227], v[52:67]
	global_load_dwordx4 v[88:91], v[248:249], off offset:384
	s_waitcnt lgkmcnt(4)
	v_mfma_f32_32x32x16_bf16 v[36:51], v[232:235], v[224:227], v[36:51]
	global_load_dwordx4 v[96:99], v[188:189], off offset:384
	s_waitcnt lgkmcnt(3)
	v_mfma_f32_32x32x16_bf16 v[20:35], v[228:231], v[236:239], v[20:35]
	v_mfma_f32_32x32x16_bf16 v[4:19], v[232:235], v[236:239], v[4:19]
	s_setprio 0
	s_waitcnt lgkmcnt(0)
	s_barrier
	ds_read_b128 v[180:183], v196
	ds_read_b128 v[184:187], v197 offset:18432
	ds_read_b128 v[216:219], v197 offset:23040
	ds_read_b128 v[220:223], v196 offset:4608
	ds_read_b128 v[224:227], v196 offset:32
	ds_read_b128 v[228:231], v197 offset:18464
	ds_read_b128 v[232:235], v197 offset:23072
	ds_read_b128 v[236:239], v196 offset:4640
	s_setprio 1
	s_waitcnt lgkmcnt(6)
	v_mfma_f32_32x32x16_bf16 v[52:67], v[184:187], v[180:183], v[52:67]
	s_waitcnt vmcnt(7)
	ds_write_b128 v195, v[68:71]
	s_waitcnt lgkmcnt(6)
	v_mfma_f32_32x32x16_bf16 v[36:51], v[216:219], v[180:183], v[36:51]
	s_waitcnt vmcnt(6)
	ds_write_b128 v195, v[76:79] offset:4608
	s_waitcnt lgkmcnt(6)
	v_mfma_f32_32x32x16_bf16 v[20:35], v[184:187], v[220:223], v[20:35]
	s_waitcnt vmcnt(5)
	ds_write_b128 v195, v[84:87] offset:9216
	global_load_dwordx4 v[68:71], v[118:119], off offset:512
	v_mfma_f32_32x32x16_bf16 v[4:19], v[216:219], v[220:223], v[4:19]
	ds_read_b128 v[180:183], v196 offset:64
	ds_read_b128 v[184:187], v197 offset:18496
	s_waitcnt lgkmcnt(7)
	v_mfma_f32_32x32x16_bf16 v[52:67], v[228:231], v[224:227], v[52:67]
	ds_read_b128 v[216:219], v197 offset:23104
	ds_read_b128 v[220:223], v196 offset:4672
	s_waitcnt lgkmcnt(8)
	v_mfma_f32_32x32x16_bf16 v[36:51], v[232:235], v[224:227], v[36:51]
	s_waitcnt vmcnt(5)
	ds_write_b128 v195, v[92:95] offset:13824
	global_load_dwordx4 v[76:79], v[240:241], off offset:512
	s_waitcnt lgkmcnt(8)
	v_mfma_f32_32x32x16_bf16 v[20:35], v[228:231], v[236:239], v[20:35]
	s_waitcnt vmcnt(5)
	ds_write_b128 v195, v[72:75] offset:18432
	global_load_dwordx4 v[84:87], v[242:243], off offset:512
	v_mfma_f32_32x32x16_bf16 v[4:19], v[232:235], v[236:239], v[4:19]
	ds_read_b128 v[224:227], v196 offset:96
	ds_read_b128 v[228:231], v197 offset:18528
	s_waitcnt lgkmcnt(6)
	v_mfma_f32_32x32x16_bf16 v[52:67], v[184:187], v[180:183], v[52:67]
	ds_read_b128 v[232:235], v197 offset:23136
	ds_read_b128 v[236:239], v196 offset:4704
	s_waitcnt lgkmcnt(7)
	v_mfma_f32_32x32x16_bf16 v[36:51], v[216:219], v[180:183], v[36:51]
	s_waitcnt vmcnt(5)
	ds_write_b128 v195, v[80:83] offset:23040
	global_load_dwordx4 v[92:95], v[244:245], off offset:512
	s_waitcnt lgkmcnt(7)
	v_mfma_f32_32x32x16_bf16 v[20:35], v[184:187], v[220:223], v[20:35]
	s_waitcnt vmcnt(5)
	ds_write_b128 v195, v[88:91] offset:27648
	global_load_dwordx4 v[72:75], v[122:123], off offset:512
	v_mfma_f32_32x32x16_bf16 v[4:19], v[216:219], v[220:223], v[4:19]
	s_waitcnt vmcnt(5)
	ds_write_b128 v195, v[96:99] offset:32256
	global_load_dwordx4 v[80:83], v[246:247], off offset:512
	s_waitcnt lgkmcnt(5)
	v_mfma_f32_32x32x16_bf16 v[52:67], v[228:231], v[224:227], v[52:67]
	global_load_dwordx4 v[88:91], v[248:249], off offset:512
	s_waitcnt lgkmcnt(4)
	v_mfma_f32_32x32x16_bf16 v[36:51], v[232:235], v[224:227], v[36:51]
	global_load_dwordx4 v[96:99], v[188:189], off offset:512
	s_waitcnt lgkmcnt(3)
	v_mfma_f32_32x32x16_bf16 v[20:35], v[228:231], v[236:239], v[20:35]
	v_mfma_f32_32x32x16_bf16 v[4:19], v[232:235], v[236:239], v[4:19]
	s_setprio 0
	s_waitcnt lgkmcnt(0)
	s_barrier
	ds_read_b128 v[180:183], v196 offset:36864
	ds_read_b128 v[184:187], v197 offset:55296
	ds_read_b128 v[216:219], v197 offset:59904
	ds_read_b128 v[220:223], v196 offset:41472
	ds_read_b128 v[224:227], v196 offset:36896
	ds_read_b128 v[228:231], v197 offset:55328
	ds_read_b128 v[232:235], v197 offset:59936
	ds_read_b128 v[236:239], v196 offset:41504
	s_setprio 1
	s_waitcnt lgkmcnt(6)
	v_mfma_f32_32x32x16_bf16 v[52:67], v[184:187], v[180:183], v[52:67]
	s_waitcnt vmcnt(7)
	ds_write_b128 v194, v[68:71]
	s_waitcnt lgkmcnt(6)
	v_mfma_f32_32x32x16_bf16 v[36:51], v[216:219], v[180:183], v[36:51]
	s_waitcnt vmcnt(6)
	ds_write_b128 v194, v[76:79] offset:4608
	s_waitcnt lgkmcnt(6)
	v_mfma_f32_32x32x16_bf16 v[20:35], v[184:187], v[220:223], v[20:35]
	s_waitcnt vmcnt(5)
	ds_write_b128 v194, v[84:87] offset:9216
	global_load_dwordx4 v[68:71], v[118:119], off offset:640
	v_mfma_f32_32x32x16_bf16 v[4:19], v[216:219], v[220:223], v[4:19]
	ds_read_b128 v[180:183], v196 offset:36928
	ds_read_b128 v[184:187], v197 offset:55360
	s_waitcnt lgkmcnt(7)
	v_mfma_f32_32x32x16_bf16 v[52:67], v[228:231], v[224:227], v[52:67]
	ds_read_b128 v[216:219], v197 offset:59968
	ds_read_b128 v[220:223], v196 offset:41536
	s_waitcnt lgkmcnt(8)
	v_mfma_f32_32x32x16_bf16 v[36:51], v[232:235], v[224:227], v[36:51]
	s_waitcnt vmcnt(5)
	ds_write_b128 v194, v[92:95] offset:13824
	global_load_dwordx4 v[76:79], v[240:241], off offset:640
	s_waitcnt lgkmcnt(8)
	v_mfma_f32_32x32x16_bf16 v[20:35], v[228:231], v[236:239], v[20:35]
	s_waitcnt vmcnt(5)
	ds_write_b128 v194, v[72:75] offset:18432
	global_load_dwordx4 v[84:87], v[242:243], off offset:640
	v_mfma_f32_32x32x16_bf16 v[4:19], v[232:235], v[236:239], v[4:19]
	ds_read_b128 v[224:227], v196 offset:36960
	ds_read_b128 v[228:231], v197 offset:55392
	s_waitcnt lgkmcnt(6)
	v_mfma_f32_32x32x16_bf16 v[52:67], v[184:187], v[180:183], v[52:67]
	ds_read_b128 v[232:235], v197 offset:60000
	ds_read_b128 v[236:239], v196 offset:41568
	s_waitcnt lgkmcnt(7)
	v_mfma_f32_32x32x16_bf16 v[36:51], v[216:219], v[180:183], v[36:51]
	s_waitcnt vmcnt(5)
	ds_write_b128 v194, v[80:83] offset:23040
	global_load_dwordx4 v[92:95], v[244:245], off offset:640
	s_waitcnt lgkmcnt(7)
	v_mfma_f32_32x32x16_bf16 v[20:35], v[184:187], v[220:223], v[20:35]
	s_waitcnt vmcnt(5)
	ds_write_b128 v194, v[88:91] offset:27648
	global_load_dwordx4 v[72:75], v[122:123], off offset:640
	v_mfma_f32_32x32x16_bf16 v[4:19], v[216:219], v[220:223], v[4:19]
	s_waitcnt vmcnt(5)
	ds_write_b128 v194, v[96:99] offset:32256
	global_load_dwordx4 v[80:83], v[246:247], off offset:640
	s_waitcnt lgkmcnt(5)
	v_mfma_f32_32x32x16_bf16 v[52:67], v[228:231], v[224:227], v[52:67]
	global_load_dwordx4 v[88:91], v[248:249], off offset:640
	s_waitcnt lgkmcnt(4)
	v_mfma_f32_32x32x16_bf16 v[36:51], v[232:235], v[224:227], v[36:51]
	global_load_dwordx4 v[96:99], v[188:189], off offset:640
	s_waitcnt lgkmcnt(3)
	v_mfma_f32_32x32x16_bf16 v[20:35], v[228:231], v[236:239], v[20:35]
	v_mfma_f32_32x32x16_bf16 v[4:19], v[232:235], v[236:239], v[4:19]
	s_setprio 0
	s_waitcnt lgkmcnt(0)
	s_barrier
	s_nop 7
	s_nop 4
	v_mov_b32_e32 v174, v141
	v_add_u32_e32 v141, 0x400, v141
	v_ashrrev_i32_e32 v175, 31, v174
	v_lshl_add_u64 v[174:175], v[174:175], 1, s[12:13]
	global_load_dwordx2 v[176:177], v[174:175], off
	s_waitcnt vmcnt(0)
	v_lshlrev_b32_e32 v178, 16, v176
	v_and_b32_e32 v179, 0xffff0000, v176
	v_fma_f32 v170, v52, v178, v170
	v_fma_f32 v171, v53, v179, v171
	v_lshlrev_b32_e32 v52, 16, v177
	v_and_b32_e32 v53, 0xffff0000, v177
	v_pk_fma_f32 v[172:173], v[54:55], v[52:53], v[172:173]
	global_load_dwordx2 v[52:53], v[174:175], off offset:16
	s_waitcnt vmcnt(0)
	v_lshlrev_b32_e32 v54, 16, v52
	v_and_b32_e32 v55, 0xffff0000, v52
	v_lshlrev_b32_e32 v52, 16, v53
	v_and_b32_e32 v53, 0xffff0000, v53
	v_pk_fma_f32 v[168:169], v[58:59], v[52:53], v[168:169]
	global_load_dwordx2 v[52:53], v[174:175], off offset:32
	v_pk_fma_f32 v[166:167], v[56:57], v[54:55], v[166:167]
	s_waitcnt vmcnt(0)
	v_lshlrev_b32_e32 v54, 16, v52
	v_and_b32_e32 v55, 0xffff0000, v52
	v_lshlrev_b32_e32 v52, 16, v53
	v_and_b32_e32 v53, 0xffff0000, v53
	v_pk_fma_f32 v[164:165], v[62:63], v[52:53], v[164:165]
	global_load_dwordx2 v[52:53], v[174:175], off offset:48
	v_pk_fma_f32 v[162:163], v[60:61], v[54:55], v[162:163]
	s_waitcnt vmcnt(0)
	v_lshlrev_b32_e32 v54, 16, v52
	v_and_b32_e32 v55, 0xffff0000, v52
	v_lshlrev_b32_e32 v52, 16, v53
	v_and_b32_e32 v53, 0xffff0000, v53
	v_pk_fma_f32 v[158:159], v[66:67], v[52:53], v[158:159]
	global_load_dwordx2 v[52:53], v[174:175], off offset:64
	v_pk_fma_f32 v[160:161], v[64:65], v[54:55], v[160:161]
	s_waitcnt vmcnt(0)
	v_lshlrev_b32_e32 v54, 16, v52
	v_and_b32_e32 v55, 0xffff0000, v52
	v_pk_fma_f32 v[154:155], v[36:37], v[54:55], v[154:155]
	v_lshlrev_b32_e32 v36, 16, v53
	v_and_b32_e32 v37, 0xffff0000, v53
	v_pk_fma_f32 v[156:157], v[38:39], v[36:37], v[156:157]
	global_load_dwordx2 v[36:37], v[174:175], off offset:80
	s_waitcnt vmcnt(0)
	v_lshlrev_b32_e32 v38, 16, v36
	v_and_b32_e32 v39, 0xffff0000, v36
	v_lshlrev_b32_e32 v36, 16, v37
	v_and_b32_e32 v37, 0xffff0000, v37
	v_pk_fma_f32 v[152:153], v[42:43], v[36:37], v[152:153]
	global_load_dwordx2 v[36:37], v[174:175], off offset:96
	v_pk_fma_f32 v[150:151], v[40:41], v[38:39], v[150:151]
	s_waitcnt vmcnt(0)
	v_lshlrev_b32_e32 v38, 16, v36
	v_and_b32_e32 v39, 0xffff0000, v36
	v_lshlrev_b32_e32 v36, 16, v37
	v_and_b32_e32 v37, 0xffff0000, v37
	v_pk_fma_f32 v[148:149], v[46:47], v[36:37], v[148:149]
	global_load_dwordx2 v[36:37], v[174:175], off offset:112
	v_pk_fma_f32 v[146:147], v[44:45], v[38:39], v[146:147]
	s_waitcnt vmcnt(0)
	v_lshlrev_b32_e32 v38, 16, v36
	v_and_b32_e32 v39, 0xffff0000, v36
	v_lshlrev_b32_e32 v36, 16, v37
	v_and_b32_e32 v37, 0xffff0000, v37
	v_pk_fma_f32 v[138:139], v[50:51], v[36:37], v[138:139]
	v_add_co_u32_e32 v36, vcc, s72, v174
	v_pk_fma_f32 v[144:145], v[48:49], v[38:39], v[144:145]
	s_nop 0
	v_addc_co_u32_e32 v37, vcc, 0, v175, vcc
	global_load_dwordx2 v[38:39], v[36:37], off
	s_waitcnt vmcnt(0)
	v_lshlrev_b32_e32 v40, 16, v38
	v_and_b32_e32 v41, 0xffff0000, v38
	v_pk_fma_f32 v[134:135], v[20:21], v[40:41], v[134:135]
	v_lshlrev_b32_e32 v20, 16, v39
	v_and_b32_e32 v21, 0xffff0000, v39
	v_pk_fma_f32 v[136:137], v[22:23], v[20:21], v[136:137]
	global_load_dwordx2 v[20:21], v[36:37], off offset:16
	s_waitcnt vmcnt(0)
	v_lshlrev_b32_e32 v22, 16, v20
	v_and_b32_e32 v23, 0xffff0000, v20
	v_lshlrev_b32_e32 v20, 16, v21
	v_and_b32_e32 v21, 0xffff0000, v21
	v_pk_fma_f32 v[132:133], v[26:27], v[20:21], v[132:133]
	global_load_dwordx2 v[20:21], v[36:37], off offset:32
	v_pk_fma_f32 v[130:131], v[24:25], v[22:23], v[130:131]
	s_waitcnt vmcnt(0)
	v_lshlrev_b32_e32 v22, 16, v20
	v_and_b32_e32 v23, 0xffff0000, v20
	v_lshlrev_b32_e32 v20, 16, v21
	v_and_b32_e32 v21, 0xffff0000, v21
	v_pk_fma_f32 v[128:129], v[30:31], v[20:21], v[128:129]
	global_load_dwordx2 v[20:21], v[36:37], off offset:48
	v_pk_fma_f32 v[126:127], v[28:29], v[22:23], v[126:127]
	s_waitcnt vmcnt(0)
	v_lshlrev_b32_e32 v22, 16, v20
	v_and_b32_e32 v23, 0xffff0000, v20
	v_lshlrev_b32_e32 v20, 16, v21
	v_and_b32_e32 v21, 0xffff0000, v21
	v_pk_fma_f32 v[120:121], v[34:35], v[20:21], v[120:121]
	global_load_dwordx2 v[20:21], v[36:37], off offset:64
	v_pk_fma_f32 v[124:125], v[32:33], v[22:23], v[124:125]
	s_waitcnt vmcnt(0)
	v_lshlrev_b32_e32 v22, 16, v20
	v_and_b32_e32 v23, 0xffff0000, v20
	v_pk_fma_f32 v[112:113], v[4:5], v[22:23], v[112:113]
	v_lshlrev_b32_e32 v4, 16, v21
	v_and_b32_e32 v5, 0xffff0000, v21
	v_pk_fma_f32 v[114:115], v[6:7], v[4:5], v[114:115]
	global_load_dwordx2 v[4:5], v[36:37], off offset:80
	s_waitcnt vmcnt(0)
	v_lshlrev_b32_e32 v6, 16, v4
	v_and_b32_e32 v7, 0xffff0000, v4
	v_lshlrev_b32_e32 v4, 16, v5
	v_and_b32_e32 v5, 0xffff0000, v5
	v_pk_fma_f32 v[110:111], v[10:11], v[4:5], v[110:111]
	global_load_dwordx2 v[4:5], v[36:37], off offset:96
	v_pk_fma_f32 v[108:109], v[8:9], v[6:7], v[108:109]
	s_waitcnt vmcnt(0)
	v_lshlrev_b32_e32 v6, 16, v4
	v_and_b32_e32 v7, 0xffff0000, v4
	v_lshlrev_b32_e32 v4, 16, v5
	v_and_b32_e32 v5, 0xffff0000, v5
	v_pk_fma_f32 v[106:107], v[14:15], v[4:5], v[106:107]
	global_load_dwordx2 v[4:5], v[36:37], off offset:112
	v_pk_fma_f32 v[104:105], v[12:13], v[6:7], v[104:105]
	s_waitcnt vmcnt(0)
	v_lshlrev_b32_e32 v6, 16, v4
	v_and_b32_e32 v7, 0xffff0000, v4
	v_lshlrev_b32_e32 v4, 16, v5
	v_and_b32_e32 v5, 0xffff0000, v5
	v_pk_fma_f32 v[102:103], v[16:17], v[6:7], v[102:103]
	v_pk_fma_f32 v[100:101], v[18:19], v[4:5], v[100:101]
	ds_read_b128 v[180:183], v196
	ds_read_b128 v[184:187], v197 offset:18432
	ds_read_b128 v[216:219], v197 offset:23040
	ds_read_b128 v[220:223], v196 offset:4608
	ds_read_b128 v[224:227], v196 offset:32
	ds_read_b128 v[228:231], v197 offset:18464
	ds_read_b128 v[232:235], v197 offset:23072
	ds_read_b128 v[236:239], v196 offset:4640
	s_setprio 1
	s_waitcnt lgkmcnt(6)
	v_mfma_f32_32x32x16_bf16 v[52:67], v[184:187], v[180:183], 0
	s_waitcnt vmcnt(7)
	ds_write_b128 v195, v[68:71]
	s_waitcnt lgkmcnt(6)
	v_mfma_f32_32x32x16_bf16 v[36:51], v[216:219], v[180:183], 0
	s_waitcnt vmcnt(6)
	ds_write_b128 v195, v[76:79] offset:4608
	s_waitcnt lgkmcnt(6)
	v_mfma_f32_32x32x16_bf16 v[20:35], v[184:187], v[220:223], 0
	s_waitcnt vmcnt(5)
	ds_write_b128 v195, v[84:87] offset:9216
	global_load_dwordx4 v[68:71], v[118:119], off offset:768
	v_mfma_f32_32x32x16_bf16 v[4:19], v[216:219], v[220:223], 0
	ds_read_b128 v[180:183], v196 offset:64
	ds_read_b128 v[184:187], v197 offset:18496
	s_waitcnt lgkmcnt(7)
	v_mfma_f32_32x32x16_bf16 v[52:67], v[228:231], v[224:227], v[52:67]
	ds_read_b128 v[216:219], v197 offset:23104
	ds_read_b128 v[220:223], v196 offset:4672
	s_waitcnt lgkmcnt(8)
	v_mfma_f32_32x32x16_bf16 v[36:51], v[232:235], v[224:227], v[36:51]
	s_waitcnt vmcnt(5)
	ds_write_b128 v195, v[92:95] offset:13824
	global_load_dwordx4 v[76:79], v[240:241], off offset:768
	s_waitcnt lgkmcnt(8)
	v_mfma_f32_32x32x16_bf16 v[20:35], v[228:231], v[236:239], v[20:35]
	s_waitcnt vmcnt(5)
	ds_write_b128 v195, v[72:75] offset:18432
	global_load_dwordx4 v[84:87], v[242:243], off offset:768
	v_mfma_f32_32x32x16_bf16 v[4:19], v[232:235], v[236:239], v[4:19]
	ds_read_b128 v[224:227], v196 offset:96
	ds_read_b128 v[228:231], v197 offset:18528
	s_waitcnt lgkmcnt(6)
	v_mfma_f32_32x32x16_bf16 v[52:67], v[184:187], v[180:183], v[52:67]
	ds_read_b128 v[232:235], v197 offset:23136
	ds_read_b128 v[236:239], v196 offset:4704
	s_waitcnt lgkmcnt(7)
	v_mfma_f32_32x32x16_bf16 v[36:51], v[216:219], v[180:183], v[36:51]
	s_waitcnt vmcnt(5)
	ds_write_b128 v195, v[80:83] offset:23040
	global_load_dwordx4 v[92:95], v[244:245], off offset:768
	s_waitcnt lgkmcnt(7)
	v_mfma_f32_32x32x16_bf16 v[20:35], v[184:187], v[220:223], v[20:35]
	s_waitcnt vmcnt(5)
	ds_write_b128 v195, v[88:91] offset:27648
	global_load_dwordx4 v[72:75], v[122:123], off offset:768
	v_mfma_f32_32x32x16_bf16 v[4:19], v[216:219], v[220:223], v[4:19]
	s_waitcnt vmcnt(5)
	ds_write_b128 v195, v[96:99] offset:32256
	global_load_dwordx4 v[80:83], v[246:247], off offset:768
	s_waitcnt lgkmcnt(5)
	v_mfma_f32_32x32x16_bf16 v[52:67], v[228:231], v[224:227], v[52:67]
	global_load_dwordx4 v[88:91], v[248:249], off offset:768
	s_waitcnt lgkmcnt(4)
	v_mfma_f32_32x32x16_bf16 v[36:51], v[232:235], v[224:227], v[36:51]
	global_load_dwordx4 v[96:99], v[188:189], off offset:768
	s_waitcnt lgkmcnt(3)
	v_mfma_f32_32x32x16_bf16 v[20:35], v[228:231], v[236:239], v[20:35]
	v_mfma_f32_32x32x16_bf16 v[4:19], v[232:235], v[236:239], v[4:19]
	s_setprio 0
	s_waitcnt lgkmcnt(0)
	s_barrier
	ds_read_b128 v[180:183], v196 offset:36864
	ds_read_b128 v[184:187], v197 offset:55296
	ds_read_b128 v[216:219], v197 offset:59904
	ds_read_b128 v[220:223], v196 offset:41472
	ds_read_b128 v[224:227], v196 offset:36896
	ds_read_b128 v[228:231], v197 offset:55328
	ds_read_b128 v[232:235], v197 offset:59936
	ds_read_b128 v[236:239], v196 offset:41504
	s_setprio 1
	s_waitcnt lgkmcnt(6)
	v_mfma_f32_32x32x16_bf16 v[52:67], v[184:187], v[180:183], v[52:67]
	s_waitcnt vmcnt(7)
	ds_write_b128 v194, v[68:71]
	s_waitcnt lgkmcnt(6)
	v_mfma_f32_32x32x16_bf16 v[36:51], v[216:219], v[180:183], v[36:51]
	s_waitcnt vmcnt(6)
	ds_write_b128 v194, v[76:79] offset:4608
	s_waitcnt lgkmcnt(6)
	v_mfma_f32_32x32x16_bf16 v[20:35], v[184:187], v[220:223], v[20:35]
	s_waitcnt vmcnt(5)
	ds_write_b128 v194, v[84:87] offset:9216
	global_load_dwordx4 v[68:71], v[118:119], off offset:896
	v_mfma_f32_32x32x16_bf16 v[4:19], v[216:219], v[220:223], v[4:19]
	ds_read_b128 v[180:183], v196 offset:36928
	ds_read_b128 v[184:187], v197 offset:55360
	s_waitcnt lgkmcnt(7)
	v_mfma_f32_32x32x16_bf16 v[52:67], v[228:231], v[224:227], v[52:67]
	ds_read_b128 v[216:219], v197 offset:59968
	ds_read_b128 v[220:223], v196 offset:41536
	s_waitcnt lgkmcnt(8)
	v_mfma_f32_32x32x16_bf16 v[36:51], v[232:235], v[224:227], v[36:51]
	s_waitcnt vmcnt(5)
	ds_write_b128 v194, v[92:95] offset:13824
	global_load_dwordx4 v[76:79], v[240:241], off offset:896
	s_waitcnt lgkmcnt(8)
	v_mfma_f32_32x32x16_bf16 v[20:35], v[228:231], v[236:239], v[20:35]
	s_waitcnt vmcnt(5)
	ds_write_b128 v194, v[72:75] offset:18432
	global_load_dwordx4 v[84:87], v[242:243], off offset:896
	v_mfma_f32_32x32x16_bf16 v[4:19], v[232:235], v[236:239], v[4:19]
	ds_read_b128 v[224:227], v196 offset:36960
	ds_read_b128 v[228:231], v197 offset:55392
	s_waitcnt lgkmcnt(6)
	v_mfma_f32_32x32x16_bf16 v[52:67], v[184:187], v[180:183], v[52:67]
	ds_read_b128 v[232:235], v197 offset:60000
	ds_read_b128 v[236:239], v196 offset:41568
	s_waitcnt lgkmcnt(7)
	v_mfma_f32_32x32x16_bf16 v[36:51], v[216:219], v[180:183], v[36:51]
	s_waitcnt vmcnt(5)
	ds_write_b128 v194, v[80:83] offset:23040
	global_load_dwordx4 v[92:95], v[244:245], off offset:896
	s_waitcnt lgkmcnt(7)
	v_mfma_f32_32x32x16_bf16 v[20:35], v[184:187], v[220:223], v[20:35]
	s_waitcnt vmcnt(5)
	ds_write_b128 v194, v[88:91] offset:27648
	global_load_dwordx4 v[72:75], v[122:123], off offset:896
	v_mfma_f32_32x32x16_bf16 v[4:19], v[216:219], v[220:223], v[4:19]
	s_waitcnt vmcnt(5)
	ds_write_b128 v194, v[96:99] offset:32256
	global_load_dwordx4 v[80:83], v[246:247], off offset:896
	s_waitcnt lgkmcnt(5)
	v_mfma_f32_32x32x16_bf16 v[52:67], v[228:231], v[224:227], v[52:67]
	global_load_dwordx4 v[88:91], v[248:249], off offset:896
	s_waitcnt lgkmcnt(4)
	v_mfma_f32_32x32x16_bf16 v[36:51], v[232:235], v[224:227], v[36:51]
	global_load_dwordx4 v[96:99], v[188:189], off offset:896
	s_waitcnt lgkmcnt(3)
	v_mfma_f32_32x32x16_bf16 v[20:35], v[228:231], v[236:239], v[20:35]
	v_mfma_f32_32x32x16_bf16 v[4:19], v[232:235], v[236:239], v[4:19]
	s_setprio 0
	s_waitcnt lgkmcnt(0)
	s_barrier
	ds_read_b128 v[180:183], v196
	ds_read_b128 v[184:187], v197 offset:18432
	ds_read_b128 v[216:219], v197 offset:23040
	ds_read_b128 v[220:223], v196 offset:4608
	ds_read_b128 v[224:227], v196 offset:32
	ds_read_b128 v[228:231], v197 offset:18464
	ds_read_b128 v[232:235], v197 offset:23072
	ds_read_b128 v[236:239], v196 offset:4640
	s_setprio 1
	s_waitcnt lgkmcnt(6)
	v_mfma_f32_32x32x16_bf16 v[52:67], v[184:187], v[180:183], v[52:67]
	s_waitcnt vmcnt(7)
	ds_write_b128 v195, v[68:71]
	s_waitcnt lgkmcnt(6)
	v_mfma_f32_32x32x16_bf16 v[36:51], v[216:219], v[180:183], v[36:51]
	s_waitcnt vmcnt(6)
	ds_write_b128 v195, v[76:79] offset:4608
	s_waitcnt lgkmcnt(6)
	v_mfma_f32_32x32x16_bf16 v[20:35], v[184:187], v[220:223], v[20:35]
	s_waitcnt vmcnt(5)
	ds_write_b128 v195, v[84:87] offset:9216
	global_load_dwordx4 v[68:71], v[118:119], off offset:1024
	v_mfma_f32_32x32x16_bf16 v[4:19], v[216:219], v[220:223], v[4:19]
	ds_read_b128 v[180:183], v196 offset:64
	ds_read_b128 v[184:187], v197 offset:18496
	s_waitcnt lgkmcnt(7)
	v_mfma_f32_32x32x16_bf16 v[52:67], v[228:231], v[224:227], v[52:67]
	ds_read_b128 v[216:219], v197 offset:23104
	ds_read_b128 v[220:223], v196 offset:4672
	s_waitcnt lgkmcnt(8)
	v_mfma_f32_32x32x16_bf16 v[36:51], v[232:235], v[224:227], v[36:51]
	s_waitcnt vmcnt(5)
	ds_write_b128 v195, v[92:95] offset:13824
	global_load_dwordx4 v[76:79], v[240:241], off offset:1024
	s_waitcnt lgkmcnt(8)
	v_mfma_f32_32x32x16_bf16 v[20:35], v[228:231], v[236:239], v[20:35]
	s_waitcnt vmcnt(5)
	ds_write_b128 v195, v[72:75] offset:18432
	global_load_dwordx4 v[84:87], v[242:243], off offset:1024
	v_mfma_f32_32x32x16_bf16 v[4:19], v[232:235], v[236:239], v[4:19]
	ds_read_b128 v[224:227], v196 offset:96
	ds_read_b128 v[228:231], v197 offset:18528
	s_waitcnt lgkmcnt(6)
	v_mfma_f32_32x32x16_bf16 v[52:67], v[184:187], v[180:183], v[52:67]
	ds_read_b128 v[232:235], v197 offset:23136
	ds_read_b128 v[236:239], v196 offset:4704
	s_waitcnt lgkmcnt(7)
	v_mfma_f32_32x32x16_bf16 v[36:51], v[216:219], v[180:183], v[36:51]
	s_waitcnt vmcnt(5)
	ds_write_b128 v195, v[80:83] offset:23040
	global_load_dwordx4 v[92:95], v[244:245], off offset:1024
	s_waitcnt lgkmcnt(7)
	v_mfma_f32_32x32x16_bf16 v[20:35], v[184:187], v[220:223], v[20:35]
	s_waitcnt vmcnt(5)
	ds_write_b128 v195, v[88:91] offset:27648
	global_load_dwordx4 v[72:75], v[122:123], off offset:1024
	v_mfma_f32_32x32x16_bf16 v[4:19], v[216:219], v[220:223], v[4:19]
	s_waitcnt vmcnt(5)
	ds_write_b128 v195, v[96:99] offset:32256
	global_load_dwordx4 v[80:83], v[246:247], off offset:1024
	s_waitcnt lgkmcnt(5)
	v_mfma_f32_32x32x16_bf16 v[52:67], v[228:231], v[224:227], v[52:67]
	global_load_dwordx4 v[88:91], v[248:249], off offset:1024
	s_waitcnt lgkmcnt(4)
	v_mfma_f32_32x32x16_bf16 v[36:51], v[232:235], v[224:227], v[36:51]
	global_load_dwordx4 v[96:99], v[188:189], off offset:1024
	s_waitcnt lgkmcnt(3)
	v_mfma_f32_32x32x16_bf16 v[20:35], v[228:231], v[236:239], v[20:35]
	v_mfma_f32_32x32x16_bf16 v[4:19], v[232:235], v[236:239], v[4:19]
	s_setprio 0
	s_waitcnt lgkmcnt(0)
	s_barrier
	ds_read_b128 v[180:183], v196 offset:36864
	ds_read_b128 v[184:187], v197 offset:55296
	ds_read_b128 v[216:219], v197 offset:59904
	ds_read_b128 v[220:223], v196 offset:41472
	ds_read_b128 v[224:227], v196 offset:36896
	ds_read_b128 v[228:231], v197 offset:55328
	ds_read_b128 v[232:235], v197 offset:59936
	ds_read_b128 v[236:239], v196 offset:41504
	s_setprio 1
	s_waitcnt lgkmcnt(6)
	v_mfma_f32_32x32x16_bf16 v[52:67], v[184:187], v[180:183], v[52:67]
	s_waitcnt vmcnt(7)
	ds_write_b128 v194, v[68:71]
	s_waitcnt lgkmcnt(6)
	v_mfma_f32_32x32x16_bf16 v[36:51], v[216:219], v[180:183], v[36:51]
	s_waitcnt vmcnt(6)
	ds_write_b128 v194, v[76:79] offset:4608
	s_waitcnt lgkmcnt(6)
	v_mfma_f32_32x32x16_bf16 v[20:35], v[184:187], v[220:223], v[20:35]
	s_waitcnt vmcnt(5)
	ds_write_b128 v194, v[84:87] offset:9216
	global_load_dwordx4 v[68:71], v[118:119], off offset:1152
	v_mfma_f32_32x32x16_bf16 v[4:19], v[216:219], v[220:223], v[4:19]
	ds_read_b128 v[180:183], v196 offset:36928
	ds_read_b128 v[184:187], v197 offset:55360
	s_waitcnt lgkmcnt(7)
	v_mfma_f32_32x32x16_bf16 v[52:67], v[228:231], v[224:227], v[52:67]
	ds_read_b128 v[216:219], v197 offset:59968
	ds_read_b128 v[220:223], v196 offset:41536
	s_waitcnt lgkmcnt(8)
	v_mfma_f32_32x32x16_bf16 v[36:51], v[232:235], v[224:227], v[36:51]
	s_waitcnt vmcnt(5)
	ds_write_b128 v194, v[92:95] offset:13824
	global_load_dwordx4 v[76:79], v[240:241], off offset:1152
	s_waitcnt lgkmcnt(8)
	v_mfma_f32_32x32x16_bf16 v[20:35], v[228:231], v[236:239], v[20:35]
	s_waitcnt vmcnt(5)
	ds_write_b128 v194, v[72:75] offset:18432
	global_load_dwordx4 v[84:87], v[242:243], off offset:1152
	v_mfma_f32_32x32x16_bf16 v[4:19], v[232:235], v[236:239], v[4:19]
	ds_read_b128 v[224:227], v196 offset:36960
	ds_read_b128 v[228:231], v197 offset:55392
	s_waitcnt lgkmcnt(6)
	v_mfma_f32_32x32x16_bf16 v[52:67], v[184:187], v[180:183], v[52:67]
	ds_read_b128 v[232:235], v197 offset:60000
	ds_read_b128 v[236:239], v196 offset:41568
	s_waitcnt lgkmcnt(7)
	v_mfma_f32_32x32x16_bf16 v[36:51], v[216:219], v[180:183], v[36:51]
	s_waitcnt vmcnt(5)
	ds_write_b128 v194, v[80:83] offset:23040
	global_load_dwordx4 v[92:95], v[244:245], off offset:1152
	s_waitcnt lgkmcnt(7)
	v_mfma_f32_32x32x16_bf16 v[20:35], v[184:187], v[220:223], v[20:35]
	s_waitcnt vmcnt(5)
	ds_write_b128 v194, v[88:91] offset:27648
	global_load_dwordx4 v[72:75], v[122:123], off offset:1152
	v_mfma_f32_32x32x16_bf16 v[4:19], v[216:219], v[220:223], v[4:19]
	s_waitcnt vmcnt(5)
	ds_write_b128 v194, v[96:99] offset:32256
	global_load_dwordx4 v[80:83], v[246:247], off offset:1152
	s_waitcnt lgkmcnt(5)
	v_mfma_f32_32x32x16_bf16 v[52:67], v[228:231], v[224:227], v[52:67]
	global_load_dwordx4 v[88:91], v[248:249], off offset:1152
	s_waitcnt lgkmcnt(4)
	v_mfma_f32_32x32x16_bf16 v[36:51], v[232:235], v[224:227], v[36:51]
	global_load_dwordx4 v[96:99], v[188:189], off offset:1152
	s_waitcnt lgkmcnt(3)
	v_mfma_f32_32x32x16_bf16 v[20:35], v[228:231], v[236:239], v[20:35]
	v_mfma_f32_32x32x16_bf16 v[4:19], v[232:235], v[236:239], v[4:19]
	s_setprio 0
	s_waitcnt lgkmcnt(0)
	s_barrier
	s_nop 7
	s_nop 4
	v_mov_b32_e32 v174, v141
	v_add_u32_e32 v141, 0x400, v141
	v_ashrrev_i32_e32 v175, 31, v174
	v_lshl_add_u64 v[174:175], v[174:175], 1, s[12:13]
	global_load_dwordx2 v[176:177], v[174:175], off
	s_waitcnt vmcnt(0)
	v_lshlrev_b32_e32 v178, 16, v176
	v_and_b32_e32 v179, 0xffff0000, v176
	v_fma_f32 v170, v52, v178, v170
	v_fma_f32 v171, v53, v179, v171
	v_lshlrev_b32_e32 v52, 16, v177
	v_and_b32_e32 v53, 0xffff0000, v177
	v_pk_fma_f32 v[172:173], v[54:55], v[52:53], v[172:173]
	global_load_dwordx2 v[52:53], v[174:175], off offset:16
	s_waitcnt vmcnt(0)
	v_lshlrev_b32_e32 v54, 16, v52
	v_and_b32_e32 v55, 0xffff0000, v52
	v_lshlrev_b32_e32 v52, 16, v53
	v_and_b32_e32 v53, 0xffff0000, v53
	v_pk_fma_f32 v[168:169], v[58:59], v[52:53], v[168:169]
	global_load_dwordx2 v[52:53], v[174:175], off offset:32
	v_pk_fma_f32 v[166:167], v[56:57], v[54:55], v[166:167]
	s_waitcnt vmcnt(0)
	v_lshlrev_b32_e32 v54, 16, v52
	v_and_b32_e32 v55, 0xffff0000, v52
	v_lshlrev_b32_e32 v52, 16, v53
	v_and_b32_e32 v53, 0xffff0000, v53
	v_pk_fma_f32 v[164:165], v[62:63], v[52:53], v[164:165]
	global_load_dwordx2 v[52:53], v[174:175], off offset:48
	v_pk_fma_f32 v[162:163], v[60:61], v[54:55], v[162:163]
	s_waitcnt vmcnt(0)
	v_lshlrev_b32_e32 v54, 16, v52
	v_and_b32_e32 v55, 0xffff0000, v52
	v_lshlrev_b32_e32 v52, 16, v53
	v_and_b32_e32 v53, 0xffff0000, v53
	v_pk_fma_f32 v[158:159], v[66:67], v[52:53], v[158:159]
	global_load_dwordx2 v[52:53], v[174:175], off offset:64
	v_pk_fma_f32 v[160:161], v[64:65], v[54:55], v[160:161]
	s_waitcnt vmcnt(0)
	v_lshlrev_b32_e32 v54, 16, v52
	v_and_b32_e32 v55, 0xffff0000, v52
	v_pk_fma_f32 v[154:155], v[36:37], v[54:55], v[154:155]
	v_lshlrev_b32_e32 v36, 16, v53
	v_and_b32_e32 v37, 0xffff0000, v53
	v_pk_fma_f32 v[156:157], v[38:39], v[36:37], v[156:157]
	global_load_dwordx2 v[36:37], v[174:175], off offset:80
	s_waitcnt vmcnt(0)
	v_lshlrev_b32_e32 v38, 16, v36
	v_and_b32_e32 v39, 0xffff0000, v36
	v_lshlrev_b32_e32 v36, 16, v37
	v_and_b32_e32 v37, 0xffff0000, v37
	v_pk_fma_f32 v[152:153], v[42:43], v[36:37], v[152:153]
	global_load_dwordx2 v[36:37], v[174:175], off offset:96
	v_pk_fma_f32 v[150:151], v[40:41], v[38:39], v[150:151]
	s_waitcnt vmcnt(0)
	v_lshlrev_b32_e32 v38, 16, v36
	v_and_b32_e32 v39, 0xffff0000, v36
	v_lshlrev_b32_e32 v36, 16, v37
	v_and_b32_e32 v37, 0xffff0000, v37
	v_pk_fma_f32 v[148:149], v[46:47], v[36:37], v[148:149]
	global_load_dwordx2 v[36:37], v[174:175], off offset:112
	v_pk_fma_f32 v[146:147], v[44:45], v[38:39], v[146:147]
	s_waitcnt vmcnt(0)
	v_lshlrev_b32_e32 v38, 16, v36
	v_and_b32_e32 v39, 0xffff0000, v36
	v_lshlrev_b32_e32 v36, 16, v37
	v_and_b32_e32 v37, 0xffff0000, v37
	v_pk_fma_f32 v[138:139], v[50:51], v[36:37], v[138:139]
	v_add_co_u32_e32 v36, vcc, s72, v174
	v_pk_fma_f32 v[144:145], v[48:49], v[38:39], v[144:145]
	s_nop 0
	v_addc_co_u32_e32 v37, vcc, 0, v175, vcc
	global_load_dwordx2 v[38:39], v[36:37], off
	s_waitcnt vmcnt(0)
	v_lshlrev_b32_e32 v40, 16, v38
	v_and_b32_e32 v41, 0xffff0000, v38
	v_pk_fma_f32 v[134:135], v[20:21], v[40:41], v[134:135]
	v_lshlrev_b32_e32 v20, 16, v39
	v_and_b32_e32 v21, 0xffff0000, v39
	v_pk_fma_f32 v[136:137], v[22:23], v[20:21], v[136:137]
	global_load_dwordx2 v[20:21], v[36:37], off offset:16
	s_waitcnt vmcnt(0)
	v_lshlrev_b32_e32 v22, 16, v20
	v_and_b32_e32 v23, 0xffff0000, v20
	v_lshlrev_b32_e32 v20, 16, v21
	v_and_b32_e32 v21, 0xffff0000, v21
	v_pk_fma_f32 v[132:133], v[26:27], v[20:21], v[132:133]
	global_load_dwordx2 v[20:21], v[36:37], off offset:32
	v_pk_fma_f32 v[130:131], v[24:25], v[22:23], v[130:131]
	s_waitcnt vmcnt(0)
	v_lshlrev_b32_e32 v22, 16, v20
	v_and_b32_e32 v23, 0xffff0000, v20
	v_lshlrev_b32_e32 v20, 16, v21
	v_and_b32_e32 v21, 0xffff0000, v21
	v_pk_fma_f32 v[128:129], v[30:31], v[20:21], v[128:129]
	global_load_dwordx2 v[20:21], v[36:37], off offset:48
	v_pk_fma_f32 v[126:127], v[28:29], v[22:23], v[126:127]
	s_waitcnt vmcnt(0)
	v_lshlrev_b32_e32 v22, 16, v20
	v_and_b32_e32 v23, 0xffff0000, v20
	v_lshlrev_b32_e32 v20, 16, v21
	v_and_b32_e32 v21, 0xffff0000, v21
	v_pk_fma_f32 v[120:121], v[34:35], v[20:21], v[120:121]
	global_load_dwordx2 v[20:21], v[36:37], off offset:64
	v_pk_fma_f32 v[124:125], v[32:33], v[22:23], v[124:125]
	s_waitcnt vmcnt(0)
	v_lshlrev_b32_e32 v22, 16, v20
	v_and_b32_e32 v23, 0xffff0000, v20
	v_pk_fma_f32 v[112:113], v[4:5], v[22:23], v[112:113]
	v_lshlrev_b32_e32 v4, 16, v21
	v_and_b32_e32 v5, 0xffff0000, v21
	v_pk_fma_f32 v[114:115], v[6:7], v[4:5], v[114:115]
	global_load_dwordx2 v[4:5], v[36:37], off offset:80
	s_waitcnt vmcnt(0)
	v_lshlrev_b32_e32 v6, 16, v4
	v_and_b32_e32 v7, 0xffff0000, v4
	v_lshlrev_b32_e32 v4, 16, v5
	v_and_b32_e32 v5, 0xffff0000, v5
	v_pk_fma_f32 v[110:111], v[10:11], v[4:5], v[110:111]
	global_load_dwordx2 v[4:5], v[36:37], off offset:96
	v_pk_fma_f32 v[108:109], v[8:9], v[6:7], v[108:109]
	s_waitcnt vmcnt(0)
	v_lshlrev_b32_e32 v6, 16, v4
	v_and_b32_e32 v7, 0xffff0000, v4
	v_lshlrev_b32_e32 v4, 16, v5
	v_and_b32_e32 v5, 0xffff0000, v5
	v_pk_fma_f32 v[106:107], v[14:15], v[4:5], v[106:107]
	global_load_dwordx2 v[4:5], v[36:37], off offset:112
	v_pk_fma_f32 v[104:105], v[12:13], v[6:7], v[104:105]
	s_waitcnt vmcnt(0)
	v_lshlrev_b32_e32 v6, 16, v4
	v_and_b32_e32 v7, 0xffff0000, v4
	v_lshlrev_b32_e32 v4, 16, v5
	v_and_b32_e32 v5, 0xffff0000, v5
	v_pk_fma_f32 v[102:103], v[16:17], v[6:7], v[102:103]
	v_pk_fma_f32 v[100:101], v[18:19], v[4:5], v[100:101]
	ds_read_b128 v[180:183], v196
	ds_read_b128 v[184:187], v197 offset:18432
	ds_read_b128 v[216:219], v197 offset:23040
	ds_read_b128 v[220:223], v196 offset:4608
	ds_read_b128 v[224:227], v196 offset:32
	ds_read_b128 v[228:231], v197 offset:18464
	ds_read_b128 v[232:235], v197 offset:23072
	ds_read_b128 v[236:239], v196 offset:4640
	s_setprio 1
	s_waitcnt lgkmcnt(6)
	v_mfma_f32_32x32x16_bf16 v[52:67], v[184:187], v[180:183], 0
	s_waitcnt vmcnt(7)
	ds_write_b128 v195, v[68:71]
	s_waitcnt lgkmcnt(6)
	v_mfma_f32_32x32x16_bf16 v[36:51], v[216:219], v[180:183], 0
	s_waitcnt vmcnt(6)
	ds_write_b128 v195, v[76:79] offset:4608
	s_waitcnt lgkmcnt(6)
	v_mfma_f32_32x32x16_bf16 v[20:35], v[184:187], v[220:223], 0
	s_waitcnt vmcnt(5)
	ds_write_b128 v195, v[84:87] offset:9216
	global_load_dwordx4 v[68:71], v[118:119], off offset:1280
	v_mfma_f32_32x32x16_bf16 v[4:19], v[216:219], v[220:223], 0
	ds_read_b128 v[180:183], v196 offset:64
	ds_read_b128 v[184:187], v197 offset:18496
	s_waitcnt lgkmcnt(7)
	v_mfma_f32_32x32x16_bf16 v[52:67], v[228:231], v[224:227], v[52:67]
	ds_read_b128 v[216:219], v197 offset:23104
	ds_read_b128 v[220:223], v196 offset:4672
	s_waitcnt lgkmcnt(8)
	v_mfma_f32_32x32x16_bf16 v[36:51], v[232:235], v[224:227], v[36:51]
	s_waitcnt vmcnt(5)
	ds_write_b128 v195, v[92:95] offset:13824
	global_load_dwordx4 v[76:79], v[240:241], off offset:1280
	s_waitcnt lgkmcnt(8)
	v_mfma_f32_32x32x16_bf16 v[20:35], v[228:231], v[236:239], v[20:35]
	s_waitcnt vmcnt(5)
	ds_write_b128 v195, v[72:75] offset:18432
	global_load_dwordx4 v[84:87], v[242:243], off offset:1280
	v_mfma_f32_32x32x16_bf16 v[4:19], v[232:235], v[236:239], v[4:19]
	ds_read_b128 v[224:227], v196 offset:96
	ds_read_b128 v[228:231], v197 offset:18528
	s_waitcnt lgkmcnt(6)
	v_mfma_f32_32x32x16_bf16 v[52:67], v[184:187], v[180:183], v[52:67]
	ds_read_b128 v[232:235], v197 offset:23136
	ds_read_b128 v[236:239], v196 offset:4704
	s_waitcnt lgkmcnt(7)
	v_mfma_f32_32x32x16_bf16 v[36:51], v[216:219], v[180:183], v[36:51]
	s_waitcnt vmcnt(5)
	ds_write_b128 v195, v[80:83] offset:23040
	global_load_dwordx4 v[92:95], v[244:245], off offset:1280
	s_waitcnt lgkmcnt(7)
	v_mfma_f32_32x32x16_bf16 v[20:35], v[184:187], v[220:223], v[20:35]
	s_waitcnt vmcnt(5)
	ds_write_b128 v195, v[88:91] offset:27648
	global_load_dwordx4 v[72:75], v[122:123], off offset:1280
	v_mfma_f32_32x32x16_bf16 v[4:19], v[216:219], v[220:223], v[4:19]
	s_waitcnt vmcnt(5)
	ds_write_b128 v195, v[96:99] offset:32256
	global_load_dwordx4 v[80:83], v[246:247], off offset:1280
	s_waitcnt lgkmcnt(5)
	v_mfma_f32_32x32x16_bf16 v[52:67], v[228:231], v[224:227], v[52:67]
	global_load_dwordx4 v[88:91], v[248:249], off offset:1280
	s_waitcnt lgkmcnt(4)
	v_mfma_f32_32x32x16_bf16 v[36:51], v[232:235], v[224:227], v[36:51]
	global_load_dwordx4 v[96:99], v[188:189], off offset:1280
	s_waitcnt lgkmcnt(3)
	v_mfma_f32_32x32x16_bf16 v[20:35], v[228:231], v[236:239], v[20:35]
	v_mfma_f32_32x32x16_bf16 v[4:19], v[232:235], v[236:239], v[4:19]
	s_setprio 0
	s_waitcnt lgkmcnt(0)
	s_barrier
	ds_read_b128 v[180:183], v196 offset:36864
	ds_read_b128 v[184:187], v197 offset:55296
	ds_read_b128 v[216:219], v197 offset:59904
	ds_read_b128 v[220:223], v196 offset:41472
	ds_read_b128 v[224:227], v196 offset:36896
	ds_read_b128 v[228:231], v197 offset:55328
	ds_read_b128 v[232:235], v197 offset:59936
	ds_read_b128 v[236:239], v196 offset:41504
	s_setprio 1
	s_waitcnt lgkmcnt(6)
	v_mfma_f32_32x32x16_bf16 v[52:67], v[184:187], v[180:183], v[52:67]
	s_waitcnt vmcnt(7)
	ds_write_b128 v194, v[68:71]
	s_waitcnt lgkmcnt(6)
	v_mfma_f32_32x32x16_bf16 v[36:51], v[216:219], v[180:183], v[36:51]
	s_waitcnt vmcnt(6)
	ds_write_b128 v194, v[76:79] offset:4608
	s_waitcnt lgkmcnt(6)
	v_mfma_f32_32x32x16_bf16 v[20:35], v[184:187], v[220:223], v[20:35]
	s_waitcnt vmcnt(5)
	ds_write_b128 v194, v[84:87] offset:9216
	global_load_dwordx4 v[68:71], v[118:119], off offset:1408
	v_mfma_f32_32x32x16_bf16 v[4:19], v[216:219], v[220:223], v[4:19]
	ds_read_b128 v[180:183], v196 offset:36928
	ds_read_b128 v[184:187], v197 offset:55360
	s_waitcnt lgkmcnt(7)
	v_mfma_f32_32x32x16_bf16 v[52:67], v[228:231], v[224:227], v[52:67]
	ds_read_b128 v[216:219], v197 offset:59968
	ds_read_b128 v[220:223], v196 offset:41536
	s_waitcnt lgkmcnt(8)
	v_mfma_f32_32x32x16_bf16 v[36:51], v[232:235], v[224:227], v[36:51]
	s_waitcnt vmcnt(5)
	ds_write_b128 v194, v[92:95] offset:13824
	global_load_dwordx4 v[76:79], v[240:241], off offset:1408
	s_waitcnt lgkmcnt(8)
	v_mfma_f32_32x32x16_bf16 v[20:35], v[228:231], v[236:239], v[20:35]
	s_waitcnt vmcnt(5)
	ds_write_b128 v194, v[72:75] offset:18432
	global_load_dwordx4 v[84:87], v[242:243], off offset:1408
	v_mfma_f32_32x32x16_bf16 v[4:19], v[232:235], v[236:239], v[4:19]
	ds_read_b128 v[224:227], v196 offset:36960
	ds_read_b128 v[228:231], v197 offset:55392
	s_waitcnt lgkmcnt(6)
	v_mfma_f32_32x32x16_bf16 v[52:67], v[184:187], v[180:183], v[52:67]
	ds_read_b128 v[232:235], v197 offset:60000
	ds_read_b128 v[236:239], v196 offset:41568
	s_waitcnt lgkmcnt(7)
	v_mfma_f32_32x32x16_bf16 v[36:51], v[216:219], v[180:183], v[36:51]
	s_waitcnt vmcnt(5)
	ds_write_b128 v194, v[80:83] offset:23040
	global_load_dwordx4 v[92:95], v[244:245], off offset:1408
	s_waitcnt lgkmcnt(7)
	v_mfma_f32_32x32x16_bf16 v[20:35], v[184:187], v[220:223], v[20:35]
	s_waitcnt vmcnt(5)
	ds_write_b128 v194, v[88:91] offset:27648
	global_load_dwordx4 v[72:75], v[122:123], off offset:1408
	v_mfma_f32_32x32x16_bf16 v[4:19], v[216:219], v[220:223], v[4:19]
	s_waitcnt vmcnt(5)
	ds_write_b128 v194, v[96:99] offset:32256
	global_load_dwordx4 v[80:83], v[246:247], off offset:1408
	s_waitcnt lgkmcnt(5)
	v_mfma_f32_32x32x16_bf16 v[52:67], v[228:231], v[224:227], v[52:67]
	global_load_dwordx4 v[88:91], v[248:249], off offset:1408
	s_waitcnt lgkmcnt(4)
	v_mfma_f32_32x32x16_bf16 v[36:51], v[232:235], v[224:227], v[36:51]
	global_load_dwordx4 v[96:99], v[188:189], off offset:1408
	s_waitcnt lgkmcnt(3)
	v_mfma_f32_32x32x16_bf16 v[20:35], v[228:231], v[236:239], v[20:35]
	v_mfma_f32_32x32x16_bf16 v[4:19], v[232:235], v[236:239], v[4:19]
	s_setprio 0
	s_waitcnt lgkmcnt(0)
	s_barrier
	ds_read_b128 v[180:183], v196
	ds_read_b128 v[184:187], v197 offset:18432
	ds_read_b128 v[216:219], v197 offset:23040
	ds_read_b128 v[220:223], v196 offset:4608
	ds_read_b128 v[224:227], v196 offset:32
	ds_read_b128 v[228:231], v197 offset:18464
	ds_read_b128 v[232:235], v197 offset:23072
	ds_read_b128 v[236:239], v196 offset:4640
	s_setprio 1
	s_waitcnt lgkmcnt(6)
	v_mfma_f32_32x32x16_bf16 v[52:67], v[184:187], v[180:183], v[52:67]
	s_waitcnt vmcnt(7)
	ds_write_b128 v195, v[68:71]
	s_waitcnt lgkmcnt(6)
	v_mfma_f32_32x32x16_bf16 v[36:51], v[216:219], v[180:183], v[36:51]
	s_waitcnt vmcnt(6)
	ds_write_b128 v195, v[76:79] offset:4608
	s_waitcnt lgkmcnt(6)
	v_mfma_f32_32x32x16_bf16 v[20:35], v[184:187], v[220:223], v[20:35]
	s_waitcnt vmcnt(5)
	ds_write_b128 v195, v[84:87] offset:9216
	global_load_dwordx4 v[68:71], v[118:119], off offset:1536
	v_mfma_f32_32x32x16_bf16 v[4:19], v[216:219], v[220:223], v[4:19]
	ds_read_b128 v[180:183], v196 offset:64
	ds_read_b128 v[184:187], v197 offset:18496
	s_waitcnt lgkmcnt(7)
	v_mfma_f32_32x32x16_bf16 v[52:67], v[228:231], v[224:227], v[52:67]
	ds_read_b128 v[216:219], v197 offset:23104
	ds_read_b128 v[220:223], v196 offset:4672
	s_waitcnt lgkmcnt(8)
	v_mfma_f32_32x32x16_bf16 v[36:51], v[232:235], v[224:227], v[36:51]
	s_waitcnt vmcnt(5)
	ds_write_b128 v195, v[92:95] offset:13824
	global_load_dwordx4 v[76:79], v[240:241], off offset:1536
	s_waitcnt lgkmcnt(8)
	v_mfma_f32_32x32x16_bf16 v[20:35], v[228:231], v[236:239], v[20:35]
	s_waitcnt vmcnt(5)
	ds_write_b128 v195, v[72:75] offset:18432
	global_load_dwordx4 v[84:87], v[242:243], off offset:1536
	v_mfma_f32_32x32x16_bf16 v[4:19], v[232:235], v[236:239], v[4:19]
	ds_read_b128 v[224:227], v196 offset:96
	ds_read_b128 v[228:231], v197 offset:18528
	s_waitcnt lgkmcnt(6)
	v_mfma_f32_32x32x16_bf16 v[52:67], v[184:187], v[180:183], v[52:67]
	ds_read_b128 v[232:235], v197 offset:23136
	ds_read_b128 v[236:239], v196 offset:4704
	s_waitcnt lgkmcnt(7)
	v_mfma_f32_32x32x16_bf16 v[36:51], v[216:219], v[180:183], v[36:51]
	s_waitcnt vmcnt(5)
	ds_write_b128 v195, v[80:83] offset:23040
	global_load_dwordx4 v[92:95], v[244:245], off offset:1536
	s_waitcnt lgkmcnt(7)
	v_mfma_f32_32x32x16_bf16 v[20:35], v[184:187], v[220:223], v[20:35]
	s_waitcnt vmcnt(5)
	ds_write_b128 v195, v[88:91] offset:27648
	global_load_dwordx4 v[72:75], v[122:123], off offset:1536
	v_mfma_f32_32x32x16_bf16 v[4:19], v[216:219], v[220:223], v[4:19]
	s_waitcnt vmcnt(5)
	ds_write_b128 v195, v[96:99] offset:32256
	global_load_dwordx4 v[80:83], v[246:247], off offset:1536
	s_waitcnt lgkmcnt(5)
	v_mfma_f32_32x32x16_bf16 v[52:67], v[228:231], v[224:227], v[52:67]
	global_load_dwordx4 v[88:91], v[248:249], off offset:1536
	s_waitcnt lgkmcnt(4)
	v_mfma_f32_32x32x16_bf16 v[36:51], v[232:235], v[224:227], v[36:51]
	global_load_dwordx4 v[96:99], v[188:189], off offset:1536
	s_waitcnt lgkmcnt(3)
	v_mfma_f32_32x32x16_bf16 v[20:35], v[228:231], v[236:239], v[20:35]
	v_mfma_f32_32x32x16_bf16 v[4:19], v[232:235], v[236:239], v[4:19]
	s_setprio 0
	s_waitcnt lgkmcnt(0)
	s_barrier
	ds_read_b128 v[180:183], v196 offset:36864
	ds_read_b128 v[184:187], v197 offset:55296
	ds_read_b128 v[216:219], v197 offset:59904
	ds_read_b128 v[220:223], v196 offset:41472
	ds_read_b128 v[224:227], v196 offset:36896
	ds_read_b128 v[228:231], v197 offset:55328
	ds_read_b128 v[232:235], v197 offset:59936
	ds_read_b128 v[236:239], v196 offset:41504
	s_setprio 1
	s_waitcnt lgkmcnt(6)
	v_mfma_f32_32x32x16_bf16 v[52:67], v[184:187], v[180:183], v[52:67]
	s_waitcnt vmcnt(7)
	ds_write_b128 v194, v[68:71]
	s_waitcnt lgkmcnt(6)
	v_mfma_f32_32x32x16_bf16 v[36:51], v[216:219], v[180:183], v[36:51]
	s_waitcnt vmcnt(6)
	ds_write_b128 v194, v[76:79] offset:4608
	s_waitcnt lgkmcnt(6)
	v_mfma_f32_32x32x16_bf16 v[20:35], v[184:187], v[220:223], v[20:35]
	s_waitcnt vmcnt(5)
	ds_write_b128 v194, v[84:87] offset:9216
	global_load_dwordx4 v[68:71], v[118:119], off offset:1664
	v_mfma_f32_32x32x16_bf16 v[4:19], v[216:219], v[220:223], v[4:19]
	ds_read_b128 v[180:183], v196 offset:36928
	ds_read_b128 v[184:187], v197 offset:55360
	s_waitcnt lgkmcnt(7)
	v_mfma_f32_32x32x16_bf16 v[52:67], v[228:231], v[224:227], v[52:67]
	ds_read_b128 v[216:219], v197 offset:59968
	ds_read_b128 v[220:223], v196 offset:41536
	s_waitcnt lgkmcnt(8)
	v_mfma_f32_32x32x16_bf16 v[36:51], v[232:235], v[224:227], v[36:51]
	s_waitcnt vmcnt(5)
	ds_write_b128 v194, v[92:95] offset:13824
	global_load_dwordx4 v[76:79], v[240:241], off offset:1664
	s_waitcnt lgkmcnt(8)
	v_mfma_f32_32x32x16_bf16 v[20:35], v[228:231], v[236:239], v[20:35]
	s_waitcnt vmcnt(5)
	ds_write_b128 v194, v[72:75] offset:18432
	global_load_dwordx4 v[84:87], v[242:243], off offset:1664
	v_mfma_f32_32x32x16_bf16 v[4:19], v[232:235], v[236:239], v[4:19]
	ds_read_b128 v[224:227], v196 offset:36960
	ds_read_b128 v[228:231], v197 offset:55392
	s_waitcnt lgkmcnt(6)
	v_mfma_f32_32x32x16_bf16 v[52:67], v[184:187], v[180:183], v[52:67]
	ds_read_b128 v[232:235], v197 offset:60000
	ds_read_b128 v[236:239], v196 offset:41568
	s_waitcnt lgkmcnt(7)
	v_mfma_f32_32x32x16_bf16 v[36:51], v[216:219], v[180:183], v[36:51]
	s_waitcnt vmcnt(5)
	ds_write_b128 v194, v[80:83] offset:23040
	global_load_dwordx4 v[92:95], v[244:245], off offset:1664
	s_waitcnt lgkmcnt(7)
	v_mfma_f32_32x32x16_bf16 v[20:35], v[184:187], v[220:223], v[20:35]
	s_waitcnt vmcnt(5)
	ds_write_b128 v194, v[88:91] offset:27648
	global_load_dwordx4 v[72:75], v[122:123], off offset:1664
	v_mfma_f32_32x32x16_bf16 v[4:19], v[216:219], v[220:223], v[4:19]
	s_waitcnt vmcnt(5)
	ds_write_b128 v194, v[96:99] offset:32256
	global_load_dwordx4 v[80:83], v[246:247], off offset:1664
	s_waitcnt lgkmcnt(5)
	v_mfma_f32_32x32x16_bf16 v[52:67], v[228:231], v[224:227], v[52:67]
	global_load_dwordx4 v[88:91], v[248:249], off offset:1664
	s_waitcnt lgkmcnt(4)
	v_mfma_f32_32x32x16_bf16 v[36:51], v[232:235], v[224:227], v[36:51]
	global_load_dwordx4 v[96:99], v[188:189], off offset:1664
	s_waitcnt lgkmcnt(3)
	v_mfma_f32_32x32x16_bf16 v[20:35], v[228:231], v[236:239], v[20:35]
	v_mfma_f32_32x32x16_bf16 v[4:19], v[232:235], v[236:239], v[4:19]
	s_setprio 0
	s_waitcnt lgkmcnt(0)
	s_barrier
	s_nop 7
	s_nop 4
	v_mov_b32_e32 v174, v141
	v_add_u32_e32 v141, 0x400, v141
	v_ashrrev_i32_e32 v175, 31, v174
	v_lshl_add_u64 v[174:175], v[174:175], 1, s[12:13]
	global_load_dwordx2 v[176:177], v[174:175], off
	s_waitcnt vmcnt(0)
	v_lshlrev_b32_e32 v178, 16, v176
	v_and_b32_e32 v179, 0xffff0000, v176
	v_fma_f32 v170, v52, v178, v170
	v_fma_f32 v171, v53, v179, v171
	v_lshlrev_b32_e32 v52, 16, v177
	v_and_b32_e32 v53, 0xffff0000, v177
	v_pk_fma_f32 v[172:173], v[54:55], v[52:53], v[172:173]
	global_load_dwordx2 v[52:53], v[174:175], off offset:16
	s_waitcnt vmcnt(0)
	v_lshlrev_b32_e32 v54, 16, v52
	v_and_b32_e32 v55, 0xffff0000, v52
	v_lshlrev_b32_e32 v52, 16, v53
	v_and_b32_e32 v53, 0xffff0000, v53
	v_pk_fma_f32 v[168:169], v[58:59], v[52:53], v[168:169]
	global_load_dwordx2 v[52:53], v[174:175], off offset:32
	v_pk_fma_f32 v[166:167], v[56:57], v[54:55], v[166:167]
	s_waitcnt vmcnt(0)
	v_lshlrev_b32_e32 v54, 16, v52
	v_and_b32_e32 v55, 0xffff0000, v52
	v_lshlrev_b32_e32 v52, 16, v53
	v_and_b32_e32 v53, 0xffff0000, v53
	v_pk_fma_f32 v[164:165], v[62:63], v[52:53], v[164:165]
	global_load_dwordx2 v[52:53], v[174:175], off offset:48
	v_pk_fma_f32 v[162:163], v[60:61], v[54:55], v[162:163]
	s_waitcnt vmcnt(0)
	v_lshlrev_b32_e32 v54, 16, v52
	v_and_b32_e32 v55, 0xffff0000, v52
	v_lshlrev_b32_e32 v52, 16, v53
	v_and_b32_e32 v53, 0xffff0000, v53
	v_pk_fma_f32 v[158:159], v[66:67], v[52:53], v[158:159]
	global_load_dwordx2 v[52:53], v[174:175], off offset:64
	v_pk_fma_f32 v[160:161], v[64:65], v[54:55], v[160:161]
	s_waitcnt vmcnt(0)
	v_lshlrev_b32_e32 v54, 16, v52
	v_and_b32_e32 v55, 0xffff0000, v52
	v_pk_fma_f32 v[154:155], v[36:37], v[54:55], v[154:155]
	v_lshlrev_b32_e32 v36, 16, v53
	v_and_b32_e32 v37, 0xffff0000, v53
	v_pk_fma_f32 v[156:157], v[38:39], v[36:37], v[156:157]
	global_load_dwordx2 v[36:37], v[174:175], off offset:80
	s_waitcnt vmcnt(0)
	v_lshlrev_b32_e32 v38, 16, v36
	v_and_b32_e32 v39, 0xffff0000, v36
	v_lshlrev_b32_e32 v36, 16, v37
	v_and_b32_e32 v37, 0xffff0000, v37
	v_pk_fma_f32 v[152:153], v[42:43], v[36:37], v[152:153]
	global_load_dwordx2 v[36:37], v[174:175], off offset:96
	v_pk_fma_f32 v[150:151], v[40:41], v[38:39], v[150:151]
	s_waitcnt vmcnt(0)
	v_lshlrev_b32_e32 v38, 16, v36
	v_and_b32_e32 v39, 0xffff0000, v36
	v_lshlrev_b32_e32 v36, 16, v37
	v_and_b32_e32 v37, 0xffff0000, v37
	v_pk_fma_f32 v[148:149], v[46:47], v[36:37], v[148:149]
	global_load_dwordx2 v[36:37], v[174:175], off offset:112
	v_pk_fma_f32 v[146:147], v[44:45], v[38:39], v[146:147]
	s_waitcnt vmcnt(0)
	v_lshlrev_b32_e32 v38, 16, v36
	v_and_b32_e32 v39, 0xffff0000, v36
	v_lshlrev_b32_e32 v36, 16, v37
	v_and_b32_e32 v37, 0xffff0000, v37
	v_pk_fma_f32 v[138:139], v[50:51], v[36:37], v[138:139]
	v_add_co_u32_e32 v36, vcc, s72, v174
	v_pk_fma_f32 v[144:145], v[48:49], v[38:39], v[144:145]
	s_nop 0
	v_addc_co_u32_e32 v37, vcc, 0, v175, vcc
	global_load_dwordx2 v[38:39], v[36:37], off
	s_waitcnt vmcnt(0)
	v_lshlrev_b32_e32 v40, 16, v38
	v_and_b32_e32 v41, 0xffff0000, v38
	v_pk_fma_f32 v[134:135], v[20:21], v[40:41], v[134:135]
	v_lshlrev_b32_e32 v20, 16, v39
	v_and_b32_e32 v21, 0xffff0000, v39
	v_pk_fma_f32 v[136:137], v[22:23], v[20:21], v[136:137]
	global_load_dwordx2 v[20:21], v[36:37], off offset:16
	s_waitcnt vmcnt(0)
	v_lshlrev_b32_e32 v22, 16, v20
	v_and_b32_e32 v23, 0xffff0000, v20
	v_lshlrev_b32_e32 v20, 16, v21
	v_and_b32_e32 v21, 0xffff0000, v21
	v_pk_fma_f32 v[132:133], v[26:27], v[20:21], v[132:133]
	global_load_dwordx2 v[20:21], v[36:37], off offset:32
	v_pk_fma_f32 v[130:131], v[24:25], v[22:23], v[130:131]
	s_waitcnt vmcnt(0)
	v_lshlrev_b32_e32 v22, 16, v20
	v_and_b32_e32 v23, 0xffff0000, v20
	v_lshlrev_b32_e32 v20, 16, v21
	v_and_b32_e32 v21, 0xffff0000, v21
	v_pk_fma_f32 v[128:129], v[30:31], v[20:21], v[128:129]
	global_load_dwordx2 v[20:21], v[36:37], off offset:48
	v_pk_fma_f32 v[126:127], v[28:29], v[22:23], v[126:127]
	s_waitcnt vmcnt(0)
	v_lshlrev_b32_e32 v22, 16, v20
	v_and_b32_e32 v23, 0xffff0000, v20
	v_lshlrev_b32_e32 v20, 16, v21
	v_and_b32_e32 v21, 0xffff0000, v21
	v_pk_fma_f32 v[120:121], v[34:35], v[20:21], v[120:121]
	global_load_dwordx2 v[20:21], v[36:37], off offset:64
	v_pk_fma_f32 v[124:125], v[32:33], v[22:23], v[124:125]
	s_waitcnt vmcnt(0)
	v_lshlrev_b32_e32 v22, 16, v20
	v_and_b32_e32 v23, 0xffff0000, v20
	v_pk_fma_f32 v[112:113], v[4:5], v[22:23], v[112:113]
	v_lshlrev_b32_e32 v4, 16, v21
	v_and_b32_e32 v5, 0xffff0000, v21
	v_pk_fma_f32 v[114:115], v[6:7], v[4:5], v[114:115]
	global_load_dwordx2 v[4:5], v[36:37], off offset:80
	s_waitcnt vmcnt(0)
	v_lshlrev_b32_e32 v6, 16, v4
	v_and_b32_e32 v7, 0xffff0000, v4
	v_lshlrev_b32_e32 v4, 16, v5
	v_and_b32_e32 v5, 0xffff0000, v5
	v_pk_fma_f32 v[110:111], v[10:11], v[4:5], v[110:111]
	global_load_dwordx2 v[4:5], v[36:37], off offset:96
	v_pk_fma_f32 v[108:109], v[8:9], v[6:7], v[108:109]
	s_waitcnt vmcnt(0)
	v_lshlrev_b32_e32 v6, 16, v4
	v_and_b32_e32 v7, 0xffff0000, v4
	v_lshlrev_b32_e32 v4, 16, v5
	v_and_b32_e32 v5, 0xffff0000, v5
	v_pk_fma_f32 v[106:107], v[14:15], v[4:5], v[106:107]
	global_load_dwordx2 v[4:5], v[36:37], off offset:112
	v_pk_fma_f32 v[104:105], v[12:13], v[6:7], v[104:105]
	s_waitcnt vmcnt(0)
	v_lshlrev_b32_e32 v6, 16, v4
	v_and_b32_e32 v7, 0xffff0000, v4
	v_lshlrev_b32_e32 v4, 16, v5
	v_and_b32_e32 v5, 0xffff0000, v5
	v_pk_fma_f32 v[102:103], v[16:17], v[6:7], v[102:103]
	v_pk_fma_f32 v[100:101], v[18:19], v[4:5], v[100:101]
	ds_read_b128 v[180:183], v196
	ds_read_b128 v[184:187], v197 offset:18432
	ds_read_b128 v[216:219], v197 offset:23040
	ds_read_b128 v[220:223], v196 offset:4608
	ds_read_b128 v[224:227], v196 offset:32
	ds_read_b128 v[228:231], v197 offset:18464
	ds_read_b128 v[232:235], v197 offset:23072
	ds_read_b128 v[236:239], v196 offset:4640
	s_setprio 1
	s_waitcnt lgkmcnt(6)
	v_mfma_f32_32x32x16_bf16 v[52:67], v[184:187], v[180:183], 0
	s_waitcnt vmcnt(7)
	ds_write_b128 v195, v[68:71]
	s_waitcnt lgkmcnt(6)
	v_mfma_f32_32x32x16_bf16 v[36:51], v[216:219], v[180:183], 0
	s_waitcnt vmcnt(6)
	ds_write_b128 v195, v[76:79] offset:4608
	s_waitcnt lgkmcnt(6)
	v_mfma_f32_32x32x16_bf16 v[20:35], v[184:187], v[220:223], 0
	s_waitcnt vmcnt(5)
	ds_write_b128 v195, v[84:87] offset:9216
	global_load_dwordx4 v[68:71], v[118:119], off offset:1792
	v_mfma_f32_32x32x16_bf16 v[4:19], v[216:219], v[220:223], 0
	ds_read_b128 v[180:183], v196 offset:64
	ds_read_b128 v[184:187], v197 offset:18496
	s_waitcnt lgkmcnt(7)
	v_mfma_f32_32x32x16_bf16 v[52:67], v[228:231], v[224:227], v[52:67]
	ds_read_b128 v[216:219], v197 offset:23104
	ds_read_b128 v[220:223], v196 offset:4672
	s_waitcnt lgkmcnt(8)
	v_mfma_f32_32x32x16_bf16 v[36:51], v[232:235], v[224:227], v[36:51]
	s_waitcnt vmcnt(5)
	ds_write_b128 v195, v[92:95] offset:13824
	global_load_dwordx4 v[76:79], v[240:241], off offset:1792
	s_waitcnt lgkmcnt(8)
	v_mfma_f32_32x32x16_bf16 v[20:35], v[228:231], v[236:239], v[20:35]
	s_waitcnt vmcnt(5)
	ds_write_b128 v195, v[72:75] offset:18432
	global_load_dwordx4 v[84:87], v[242:243], off offset:1792
	v_mfma_f32_32x32x16_bf16 v[4:19], v[232:235], v[236:239], v[4:19]
	ds_read_b128 v[224:227], v196 offset:96
	ds_read_b128 v[228:231], v197 offset:18528
	s_waitcnt lgkmcnt(6)
	v_mfma_f32_32x32x16_bf16 v[52:67], v[184:187], v[180:183], v[52:67]
	ds_read_b128 v[232:235], v197 offset:23136
	ds_read_b128 v[236:239], v196 offset:4704
	s_waitcnt lgkmcnt(7)
	v_mfma_f32_32x32x16_bf16 v[36:51], v[216:219], v[180:183], v[36:51]
	s_waitcnt vmcnt(5)
	ds_write_b128 v195, v[80:83] offset:23040
	global_load_dwordx4 v[92:95], v[244:245], off offset:1792
	s_waitcnt lgkmcnt(7)
	v_mfma_f32_32x32x16_bf16 v[20:35], v[184:187], v[220:223], v[20:35]
	s_waitcnt vmcnt(5)
	ds_write_b128 v195, v[88:91] offset:27648
	global_load_dwordx4 v[72:75], v[122:123], off offset:1792
	v_mfma_f32_32x32x16_bf16 v[4:19], v[216:219], v[220:223], v[4:19]
	s_waitcnt vmcnt(5)
	ds_write_b128 v195, v[96:99] offset:32256
	global_load_dwordx4 v[80:83], v[246:247], off offset:1792
	s_waitcnt lgkmcnt(5)
	v_mfma_f32_32x32x16_bf16 v[52:67], v[228:231], v[224:227], v[52:67]
	global_load_dwordx4 v[88:91], v[248:249], off offset:1792
	s_waitcnt lgkmcnt(4)
	v_mfma_f32_32x32x16_bf16 v[36:51], v[232:235], v[224:227], v[36:51]
	global_load_dwordx4 v[96:99], v[188:189], off offset:1792
	s_waitcnt lgkmcnt(3)
	v_mfma_f32_32x32x16_bf16 v[20:35], v[228:231], v[236:239], v[20:35]
	v_mfma_f32_32x32x16_bf16 v[4:19], v[232:235], v[236:239], v[4:19]
	s_setprio 0
	s_waitcnt lgkmcnt(0)
	s_barrier
	ds_read_b128 v[180:183], v196 offset:36864
	ds_read_b128 v[184:187], v197 offset:55296
	ds_read_b128 v[216:219], v197 offset:59904
	ds_read_b128 v[220:223], v196 offset:41472
	ds_read_b128 v[224:227], v196 offset:36896
	ds_read_b128 v[228:231], v197 offset:55328
	ds_read_b128 v[232:235], v197 offset:59936
	ds_read_b128 v[236:239], v196 offset:41504
	s_setprio 1
	s_waitcnt lgkmcnt(6)
	v_mfma_f32_32x32x16_bf16 v[52:67], v[184:187], v[180:183], v[52:67]
	s_waitcnt vmcnt(7)
	ds_write_b128 v194, v[68:71]
	s_waitcnt lgkmcnt(6)
	v_mfma_f32_32x32x16_bf16 v[36:51], v[216:219], v[180:183], v[36:51]
	s_waitcnt vmcnt(6)
	ds_write_b128 v194, v[76:79] offset:4608
	s_waitcnt lgkmcnt(6)
	v_mfma_f32_32x32x16_bf16 v[20:35], v[184:187], v[220:223], v[20:35]
	s_waitcnt vmcnt(5)
	ds_write_b128 v194, v[84:87] offset:9216
	global_load_dwordx4 v[68:71], v[118:119], off offset:1920
	v_mfma_f32_32x32x16_bf16 v[4:19], v[216:219], v[220:223], v[4:19]
	ds_read_b128 v[180:183], v196 offset:36928
	ds_read_b128 v[184:187], v197 offset:55360
	s_waitcnt lgkmcnt(7)
	v_mfma_f32_32x32x16_bf16 v[52:67], v[228:231], v[224:227], v[52:67]
	ds_read_b128 v[216:219], v197 offset:59968
	ds_read_b128 v[220:223], v196 offset:41536
	s_waitcnt lgkmcnt(8)
	v_mfma_f32_32x32x16_bf16 v[36:51], v[232:235], v[224:227], v[36:51]
	s_waitcnt vmcnt(5)
	ds_write_b128 v194, v[92:95] offset:13824
	global_load_dwordx4 v[76:79], v[240:241], off offset:1920
	s_waitcnt lgkmcnt(8)
	v_mfma_f32_32x32x16_bf16 v[20:35], v[228:231], v[236:239], v[20:35]
	s_waitcnt vmcnt(5)
	ds_write_b128 v194, v[72:75] offset:18432
	global_load_dwordx4 v[84:87], v[242:243], off offset:1920
	v_mfma_f32_32x32x16_bf16 v[4:19], v[232:235], v[236:239], v[4:19]
	ds_read_b128 v[224:227], v196 offset:36960
	ds_read_b128 v[228:231], v197 offset:55392
	s_waitcnt lgkmcnt(6)
	v_mfma_f32_32x32x16_bf16 v[52:67], v[184:187], v[180:183], v[52:67]
	ds_read_b128 v[232:235], v197 offset:60000
	ds_read_b128 v[236:239], v196 offset:41568
	s_waitcnt lgkmcnt(7)
	v_mfma_f32_32x32x16_bf16 v[36:51], v[216:219], v[180:183], v[36:51]
	s_waitcnt vmcnt(5)
	ds_write_b128 v194, v[80:83] offset:23040
	global_load_dwordx4 v[92:95], v[244:245], off offset:1920
	s_waitcnt lgkmcnt(7)
	v_mfma_f32_32x32x16_bf16 v[20:35], v[184:187], v[220:223], v[20:35]
	s_waitcnt vmcnt(5)
	ds_write_b128 v194, v[88:91] offset:27648
	global_load_dwordx4 v[72:75], v[122:123], off offset:1920
	v_mfma_f32_32x32x16_bf16 v[4:19], v[216:219], v[220:223], v[4:19]
	s_waitcnt vmcnt(5)
	ds_write_b128 v194, v[96:99] offset:32256
	global_load_dwordx4 v[80:83], v[246:247], off offset:1920
	s_waitcnt lgkmcnt(5)
	v_mfma_f32_32x32x16_bf16 v[52:67], v[228:231], v[224:227], v[52:67]
	global_load_dwordx4 v[88:91], v[248:249], off offset:1920
	s_waitcnt lgkmcnt(4)
	v_mfma_f32_32x32x16_bf16 v[36:51], v[232:235], v[224:227], v[36:51]
	global_load_dwordx4 v[96:99], v[188:189], off offset:1920
	s_waitcnt lgkmcnt(3)
	v_mfma_f32_32x32x16_bf16 v[20:35], v[228:231], v[236:239], v[20:35]
	v_mfma_f32_32x32x16_bf16 v[4:19], v[232:235], v[236:239], v[4:19]
	s_setprio 0
	s_waitcnt lgkmcnt(0)
	s_barrier
	ds_read_b128 v[180:183], v196
	ds_read_b128 v[184:187], v197 offset:18432
	ds_read_b128 v[216:219], v197 offset:23040
	ds_read_b128 v[220:223], v196 offset:4608
	ds_read_b128 v[224:227], v196 offset:32
	ds_read_b128 v[228:231], v197 offset:18464
	ds_read_b128 v[232:235], v197 offset:23072
	ds_read_b128 v[236:239], v196 offset:4640
	s_setprio 1
	s_waitcnt lgkmcnt(6)
	v_mfma_f32_32x32x16_bf16 v[52:67], v[184:187], v[180:183], v[52:67]
	s_waitcnt vmcnt(7)
	ds_write_b128 v195, v[68:71]
	s_waitcnt lgkmcnt(6)
	v_mfma_f32_32x32x16_bf16 v[36:51], v[216:219], v[180:183], v[36:51]
	s_waitcnt vmcnt(6)
	ds_write_b128 v195, v[76:79] offset:4608
	s_waitcnt lgkmcnt(6)
	v_mfma_f32_32x32x16_bf16 v[20:35], v[184:187], v[220:223], v[20:35]
	s_waitcnt vmcnt(5)
	ds_write_b128 v195, v[84:87] offset:9216
	v_mfma_f32_32x32x16_bf16 v[4:19], v[216:219], v[220:223], v[4:19]
	ds_read_b128 v[180:183], v196 offset:64
	ds_read_b128 v[184:187], v197 offset:18496
	s_waitcnt lgkmcnt(7)
	v_mfma_f32_32x32x16_bf16 v[52:67], v[228:231], v[224:227], v[52:67]
	ds_read_b128 v[216:219], v197 offset:23104
	ds_read_b128 v[220:223], v196 offset:4672
	s_waitcnt lgkmcnt(8)
	v_mfma_f32_32x32x16_bf16 v[36:51], v[232:235], v[224:227], v[36:51]
	s_waitcnt vmcnt(4)
	ds_write_b128 v195, v[92:95] offset:13824
	s_waitcnt lgkmcnt(8)
	v_mfma_f32_32x32x16_bf16 v[20:35], v[228:231], v[236:239], v[20:35]
	s_waitcnt vmcnt(3)
	ds_write_b128 v195, v[72:75] offset:18432
	v_mfma_f32_32x32x16_bf16 v[4:19], v[232:235], v[236:239], v[4:19]
	ds_read_b128 v[224:227], v196 offset:96
	ds_read_b128 v[228:231], v197 offset:18528
	s_waitcnt lgkmcnt(6)
	v_mfma_f32_32x32x16_bf16 v[52:67], v[184:187], v[180:183], v[52:67]
	ds_read_b128 v[232:235], v197 offset:23136
	ds_read_b128 v[236:239], v196 offset:4704
	s_waitcnt lgkmcnt(7)
	v_mfma_f32_32x32x16_bf16 v[36:51], v[216:219], v[180:183], v[36:51]
	s_waitcnt vmcnt(2)
	ds_write_b128 v195, v[80:83] offset:23040
	s_waitcnt lgkmcnt(7)
	v_mfma_f32_32x32x16_bf16 v[20:35], v[184:187], v[220:223], v[20:35]
	s_waitcnt vmcnt(1)
	ds_write_b128 v195, v[88:91] offset:27648
	v_mfma_f32_32x32x16_bf16 v[4:19], v[216:219], v[220:223], v[4:19]
	s_waitcnt vmcnt(0)
	ds_write_b128 v195, v[96:99] offset:32256
	s_waitcnt lgkmcnt(5)
	v_mfma_f32_32x32x16_bf16 v[52:67], v[228:231], v[224:227], v[52:67]
	s_waitcnt lgkmcnt(4)
	v_mfma_f32_32x32x16_bf16 v[36:51], v[232:235], v[224:227], v[36:51]
	s_waitcnt lgkmcnt(3)
	v_mfma_f32_32x32x16_bf16 v[20:35], v[228:231], v[236:239], v[20:35]
	v_mfma_f32_32x32x16_bf16 v[4:19], v[232:235], v[236:239], v[4:19]
	s_setprio 0
	s_waitcnt lgkmcnt(0)
	s_barrier
	ds_read_b128 v[180:183], v196 offset:36864
	ds_read_b128 v[184:187], v197 offset:55296
	ds_read_b128 v[216:219], v197 offset:59904
	ds_read_b128 v[220:223], v196 offset:41472
	ds_read_b128 v[224:227], v196 offset:36896
	ds_read_b128 v[228:231], v197 offset:55328
	ds_read_b128 v[232:235], v197 offset:59936
	ds_read_b128 v[236:239], v196 offset:41504
	s_setprio 1
	s_waitcnt lgkmcnt(6)
	v_mfma_f32_32x32x16_bf16 v[52:67], v[184:187], v[180:183], v[52:67]
	s_waitcnt lgkmcnt(5)
	v_mfma_f32_32x32x16_bf16 v[36:51], v[216:219], v[180:183], v[36:51]
	s_waitcnt lgkmcnt(4)
	v_mfma_f32_32x32x16_bf16 v[20:35], v[184:187], v[220:223], v[20:35]
	v_mfma_f32_32x32x16_bf16 v[4:19], v[216:219], v[220:223], v[4:19]
	ds_read_b128 v[180:183], v196 offset:36928
	ds_read_b128 v[184:187], v197 offset:55360
	s_waitcnt lgkmcnt(4)
	v_mfma_f32_32x32x16_bf16 v[52:67], v[228:231], v[224:227], v[52:67]
	ds_read_b128 v[216:219], v197 offset:59968
	ds_read_b128 v[220:223], v196 offset:41536
	s_waitcnt lgkmcnt(5)
	v_mfma_f32_32x32x16_bf16 v[36:51], v[232:235], v[224:227], v[36:51]
	s_waitcnt lgkmcnt(4)
	v_mfma_f32_32x32x16_bf16 v[20:35], v[228:231], v[236:239], v[20:35]
	v_mfma_f32_32x32x16_bf16 v[4:19], v[232:235], v[236:239], v[4:19]
	ds_read_b128 v[224:227], v196 offset:36960
	ds_read_b128 v[228:231], v197 offset:55392
	s_waitcnt lgkmcnt(4)
	v_mfma_f32_32x32x16_bf16 v[52:67], v[184:187], v[180:183], v[52:67]
	ds_read_b128 v[232:235], v197 offset:60000
	ds_read_b128 v[236:239], v196 offset:41568
	s_waitcnt lgkmcnt(5)
	v_mfma_f32_32x32x16_bf16 v[36:51], v[216:219], v[180:183], v[36:51]
	s_waitcnt lgkmcnt(4)
	v_mfma_f32_32x32x16_bf16 v[20:35], v[184:187], v[220:223], v[20:35]
	v_mfma_f32_32x32x16_bf16 v[4:19], v[216:219], v[220:223], v[4:19]
	s_waitcnt lgkmcnt(2)
	v_mfma_f32_32x32x16_bf16 v[52:67], v[228:231], v[224:227], v[52:67]
	s_waitcnt lgkmcnt(1)
	v_mfma_f32_32x32x16_bf16 v[36:51], v[232:235], v[224:227], v[36:51]
	s_waitcnt lgkmcnt(0)
	v_mfma_f32_32x32x16_bf16 v[20:35], v[228:231], v[236:239], v[20:35]
	v_mfma_f32_32x32x16_bf16 v[4:19], v[232:235], v[236:239], v[4:19]
	s_setprio 0
	s_nop 7
	s_nop 4
	v_mov_b32_e32 v174, v141
	v_add_u32_e32 v141, 0x400, v141
	v_ashrrev_i32_e32 v175, 31, v174
	v_lshl_add_u64 v[174:175], v[174:175], 1, s[12:13]
	global_load_dwordx2 v[176:177], v[174:175], off
	s_waitcnt vmcnt(0)
	v_lshlrev_b32_e32 v178, 16, v176
	v_and_b32_e32 v179, 0xffff0000, v176
	v_fma_f32 v170, v52, v178, v170
	v_fma_f32 v171, v53, v179, v171
	v_lshlrev_b32_e32 v52, 16, v177
	v_and_b32_e32 v53, 0xffff0000, v177
	v_pk_fma_f32 v[172:173], v[54:55], v[52:53], v[172:173]
	global_load_dwordx2 v[52:53], v[174:175], off offset:16
	s_waitcnt vmcnt(0)
	v_lshlrev_b32_e32 v54, 16, v52
	v_and_b32_e32 v55, 0xffff0000, v52
	v_lshlrev_b32_e32 v52, 16, v53
	v_and_b32_e32 v53, 0xffff0000, v53
	v_pk_fma_f32 v[168:169], v[58:59], v[52:53], v[168:169]
	global_load_dwordx2 v[52:53], v[174:175], off offset:32
	v_pk_fma_f32 v[166:167], v[56:57], v[54:55], v[166:167]
	s_waitcnt vmcnt(0)
	v_lshlrev_b32_e32 v54, 16, v52
	v_and_b32_e32 v55, 0xffff0000, v52
	v_lshlrev_b32_e32 v52, 16, v53
	v_and_b32_e32 v53, 0xffff0000, v53
	v_pk_fma_f32 v[164:165], v[62:63], v[52:53], v[164:165]
	global_load_dwordx2 v[52:53], v[174:175], off offset:48
	v_pk_fma_f32 v[162:163], v[60:61], v[54:55], v[162:163]
	s_waitcnt vmcnt(0)
	v_lshlrev_b32_e32 v54, 16, v52
	v_and_b32_e32 v55, 0xffff0000, v52
	v_lshlrev_b32_e32 v52, 16, v53
	v_and_b32_e32 v53, 0xffff0000, v53
	v_pk_fma_f32 v[158:159], v[66:67], v[52:53], v[158:159]
	global_load_dwordx2 v[52:53], v[174:175], off offset:64
	v_pk_fma_f32 v[160:161], v[64:65], v[54:55], v[160:161]
	s_waitcnt vmcnt(0)
	v_lshlrev_b32_e32 v54, 16, v52
	v_and_b32_e32 v55, 0xffff0000, v52
	v_pk_fma_f32 v[154:155], v[36:37], v[54:55], v[154:155]
	v_lshlrev_b32_e32 v36, 16, v53
	v_and_b32_e32 v37, 0xffff0000, v53
	v_pk_fma_f32 v[156:157], v[38:39], v[36:37], v[156:157]
	global_load_dwordx2 v[36:37], v[174:175], off offset:80
	s_waitcnt vmcnt(0)
	v_lshlrev_b32_e32 v38, 16, v36
	v_and_b32_e32 v39, 0xffff0000, v36
	v_lshlrev_b32_e32 v36, 16, v37
	v_and_b32_e32 v37, 0xffff0000, v37
	v_pk_fma_f32 v[152:153], v[42:43], v[36:37], v[152:153]
	global_load_dwordx2 v[36:37], v[174:175], off offset:96
	v_pk_fma_f32 v[150:151], v[40:41], v[38:39], v[150:151]
	s_waitcnt vmcnt(0)
	v_lshlrev_b32_e32 v38, 16, v36
	v_and_b32_e32 v39, 0xffff0000, v36
	v_lshlrev_b32_e32 v36, 16, v37
	v_and_b32_e32 v37, 0xffff0000, v37
	v_pk_fma_f32 v[148:149], v[46:47], v[36:37], v[148:149]
	global_load_dwordx2 v[36:37], v[174:175], off offset:112
	v_pk_fma_f32 v[146:147], v[44:45], v[38:39], v[146:147]
	s_waitcnt vmcnt(0)
	v_lshlrev_b32_e32 v38, 16, v36
	v_and_b32_e32 v39, 0xffff0000, v36
	v_lshlrev_b32_e32 v36, 16, v37
	v_and_b32_e32 v37, 0xffff0000, v37
	v_pk_fma_f32 v[138:139], v[50:51], v[36:37], v[138:139]
	v_add_co_u32_e32 v36, vcc, s72, v174
	v_pk_fma_f32 v[144:145], v[48:49], v[38:39], v[144:145]
	s_nop 0
	v_addc_co_u32_e32 v37, vcc, 0, v175, vcc
	global_load_dwordx2 v[38:39], v[36:37], off
	s_waitcnt vmcnt(0)
	v_lshlrev_b32_e32 v40, 16, v38
	v_and_b32_e32 v41, 0xffff0000, v38
	v_pk_fma_f32 v[134:135], v[20:21], v[40:41], v[134:135]
	v_lshlrev_b32_e32 v20, 16, v39
	v_and_b32_e32 v21, 0xffff0000, v39
	v_pk_fma_f32 v[136:137], v[22:23], v[20:21], v[136:137]
	global_load_dwordx2 v[20:21], v[36:37], off offset:16
	s_waitcnt vmcnt(0)
	v_lshlrev_b32_e32 v22, 16, v20
	v_and_b32_e32 v23, 0xffff0000, v20
	v_lshlrev_b32_e32 v20, 16, v21
	v_and_b32_e32 v21, 0xffff0000, v21
	v_pk_fma_f32 v[132:133], v[26:27], v[20:21], v[132:133]
	global_load_dwordx2 v[20:21], v[36:37], off offset:32
	v_pk_fma_f32 v[130:131], v[24:25], v[22:23], v[130:131]
	s_waitcnt vmcnt(0)
	v_lshlrev_b32_e32 v22, 16, v20
	v_and_b32_e32 v23, 0xffff0000, v20
	v_lshlrev_b32_e32 v20, 16, v21
	v_and_b32_e32 v21, 0xffff0000, v21
	v_pk_fma_f32 v[128:129], v[30:31], v[20:21], v[128:129]
	global_load_dwordx2 v[20:21], v[36:37], off offset:48
	v_pk_fma_f32 v[126:127], v[28:29], v[22:23], v[126:127]
	s_waitcnt vmcnt(0)
	v_lshlrev_b32_e32 v22, 16, v20
	v_and_b32_e32 v23, 0xffff0000, v20
	v_lshlrev_b32_e32 v20, 16, v21
	v_and_b32_e32 v21, 0xffff0000, v21
	v_pk_fma_f32 v[120:121], v[34:35], v[20:21], v[120:121]
	global_load_dwordx2 v[20:21], v[36:37], off offset:64
	v_pk_fma_f32 v[124:125], v[32:33], v[22:23], v[124:125]
	s_waitcnt vmcnt(0)
	v_lshlrev_b32_e32 v22, 16, v20
	v_and_b32_e32 v23, 0xffff0000, v20
	v_pk_fma_f32 v[112:113], v[4:5], v[22:23], v[112:113]
	v_lshlrev_b32_e32 v4, 16, v21
	v_and_b32_e32 v5, 0xffff0000, v21
	v_pk_fma_f32 v[114:115], v[6:7], v[4:5], v[114:115]
	global_load_dwordx2 v[4:5], v[36:37], off offset:80
	s_waitcnt vmcnt(0)
	v_lshlrev_b32_e32 v6, 16, v4
	v_and_b32_e32 v7, 0xffff0000, v4
	v_lshlrev_b32_e32 v4, 16, v5
	v_and_b32_e32 v5, 0xffff0000, v5
	v_pk_fma_f32 v[110:111], v[10:11], v[4:5], v[110:111]
	global_load_dwordx2 v[4:5], v[36:37], off offset:96
	v_pk_fma_f32 v[108:109], v[8:9], v[6:7], v[108:109]
	s_waitcnt vmcnt(0)
	v_lshlrev_b32_e32 v6, 16, v4
	v_and_b32_e32 v7, 0xffff0000, v4
	v_lshlrev_b32_e32 v4, 16, v5
	v_and_b32_e32 v5, 0xffff0000, v5
	v_pk_fma_f32 v[106:107], v[14:15], v[4:5], v[106:107]
	global_load_dwordx2 v[4:5], v[36:37], off offset:112
	v_pk_fma_f32 v[104:105], v[12:13], v[6:7], v[104:105]
	s_waitcnt vmcnt(0)
	v_lshlrev_b32_e32 v6, 16, v4
	v_and_b32_e32 v7, 0xffff0000, v4
	v_lshlrev_b32_e32 v4, 16, v5
	v_and_b32_e32 v5, 0xffff0000, v5
	v_pk_fma_f32 v[102:103], v[16:17], v[6:7], v[102:103]
	v_pk_fma_f32 v[100:101], v[18:19], v[4:5], v[100:101]
	s_nop 7
	s_nop 4
	v_ashrrev_i32_e32 v117, 31, v116
	v_readlane_b32 s12, v252, 62
	s_ashr_i32 s5, s4, 31
	v_lshlrev_b64 v[4:5], 11, v[116:117]
	v_readlane_b32 s14, v253, 0
	v_readlane_b32 s15, v253, 1
	s_lshl_b64 s[4:5], s[4:5], 1
	v_lshlrev_b32_e32 v2, 1, v213
	v_lshl_add_u64 v[4:5], s[14:15], 0, v[4:5]
	v_lshl_add_u64 v[4:5], v[4:5], 0, s[4:5]
	v_lshl_add_u64 v[4:5], v[4:5], 0, v[2:3]
	v_lshlrev_b32_e32 v6, 2, v214
	v_mov_b32_e32 v7, v3
	v_lshl_add_u64 v[4:5], v[4:5], 0, v[6:7]
	v_cvt_pk_bf16_f32 v8, v170, v171
	v_cvt_pk_bf16_f32 v9, v172, v173
	v_cvt_pk_bf16_f32 v10, v166, v167
	v_cvt_pk_bf16_f32 v11, v168, v169
	v_cvt_pk_bf16_f32 v12, v162, v163
	v_cvt_pk_bf16_f32 v13, v164, v165
	v_cvt_pk_bf16_f32 v14, v160, v161
	v_cvt_pk_bf16_f32 v15, v158, v159
	s_nop 1
	v_permlane32_swap_b32_e32 v8, v10
	v_permlane32_swap_b32_e32 v9, v11
	v_permlane32_swap_b32_e32 v12, v14
	v_permlane32_swap_b32_e32 v13, v15
	global_store_dwordx4 v[4:5], v[8:11], off
	global_store_dwordx4 v[4:5], v[12:15], off offset:32
	v_cvt_pk_bf16_f32 v16, v154, v155
	v_cvt_pk_bf16_f32 v17, v156, v157
	v_cvt_pk_bf16_f32 v18, v150, v151
	v_cvt_pk_bf16_f32 v19, v152, v153
	v_cvt_pk_bf16_f32 v20, v146, v147
	v_cvt_pk_bf16_f32 v21, v148, v149
	v_cvt_pk_bf16_f32 v22, v144, v145
	v_cvt_pk_bf16_f32 v23, v138, v139
	s_nop 1
	v_permlane32_swap_b32_e32 v16, v18
	v_permlane32_swap_b32_e32 v17, v19
	v_permlane32_swap_b32_e32 v20, v22
	v_permlane32_swap_b32_e32 v21, v23
	global_store_dwordx4 v[4:5], v[16:19], off offset:64
	global_store_dwordx4 v[4:5], v[20:23], off offset:96
	v_or_b32_e32 v4, 32, v116
	v_ashrrev_i32_e32 v5, 31, v4
	v_lshlrev_b64 v[4:5], 11, v[4:5]
	v_lshl_add_u64 v[4:5], s[14:15], 0, v[4:5]
	v_lshl_add_u64 v[4:5], v[4:5], 0, s[4:5]
	v_lshl_add_u64 v[4:5], v[4:5], 0, v[2:3]
	v_lshl_add_u64 v[4:5], v[4:5], 0, v[6:7]
	v_cvt_pk_bf16_f32 v24, v134, v135
	v_cvt_pk_bf16_f32 v25, v136, v137
	v_cvt_pk_bf16_f32 v26, v130, v131
	v_cvt_pk_bf16_f32 v27, v132, v133
	v_cvt_pk_bf16_f32 v28, v126, v127
	v_cvt_pk_bf16_f32 v29, v128, v129
	v_cvt_pk_bf16_f32 v30, v124, v125
	v_cvt_pk_bf16_f32 v31, v120, v121
	s_nop 1
	v_permlane32_swap_b32_e32 v24, v26
	v_permlane32_swap_b32_e32 v25, v27
	v_permlane32_swap_b32_e32 v28, v30
	v_permlane32_swap_b32_e32 v29, v31
	global_store_dwordx4 v[4:5], v[24:27], off
	global_store_dwordx4 v[4:5], v[28:31], off offset:32
	v_cvt_pk_bf16_f32 v32, v112, v113
	v_cvt_pk_bf16_f32 v33, v114, v115
	v_cvt_pk_bf16_f32 v34, v108, v109
	v_cvt_pk_bf16_f32 v35, v110, v111
	v_cvt_pk_bf16_f32 v36, v104, v105
	v_cvt_pk_bf16_f32 v37, v106, v107
	v_cvt_pk_bf16_f32 v38, v102, v103
	v_cvt_pk_bf16_f32 v39, v100, v101
	s_nop 1
	v_permlane32_swap_b32_e32 v32, v34
	v_permlane32_swap_b32_e32 v33, v35
	v_permlane32_swap_b32_e32 v36, v38
	v_permlane32_swap_b32_e32 v37, v39
	global_store_dwordx4 v[4:5], v[32:35], off offset:64
	global_store_dwordx4 v[4:5], v[36:39], off offset:96
	s_load_dword s4, s[62:63], 0x0
	v_readlane_b32 s13, v252, 63
	s_waitcnt lgkmcnt(0)
	s_add_i32 s8, s4, s8
	s_cmpk_gt_i32 s8, 0x1ff
	s_cbranch_scc0 .LBB0_62
